# handoff2 + nt on GEMM epilogue output stores
# speedup vs baseline: 1.0876x; 1.0876x over previous
.LBB0_201:
	v_pk_mul_f32 v[8:9], v[160:161], s[26:27] op_sel_hi:[1,0]
	v_pk_mul_f32 v[10:11], v[158:159], s[26:27] op_sel_hi:[1,0]
	v_pk_mul_f32 v[12:13], v[156:157], s[26:27] op_sel_hi:[1,0]
	v_exp_f32_e32 v8, v8
	v_exp_f32_e32 v9, v9
	v_pk_mul_f32 v[14:15], v[154:155], s[26:27] op_sel_hi:[1,0]
	v_exp_f32_e32 v10, v10
	v_exp_f32_e32 v11, v11
	v_exp_f32_e32 v12, v12
	v_exp_f32_e32 v13, v13
	v_exp_f32_e32 v14, v14
	v_exp_f32_e32 v15, v15
	v_pk_add_f32 v[8:9], v[8:9], 1.0 op_sel_hi:[1,0]
	v_pk_add_f32 v[10:11], v[10:11], 1.0 op_sel_hi:[1,0]
	v_pk_add_f32 v[12:13], v[12:13], 1.0 op_sel_hi:[1,0]
	v_rcp_f32_e32 v8, v8
	v_rcp_f32_e32 v9, v9
	v_pk_add_f32 v[14:15], v[14:15], 1.0 op_sel_hi:[1,0]
	v_rcp_f32_e32 v10, v10
	v_rcp_f32_e32 v11, v11
	v_rcp_f32_e32 v12, v12
	v_rcp_f32_e32 v13, v13
	v_rcp_f32_e32 v14, v14
	v_rcp_f32_e32 v15, v15
	v_pk_mul_f32 v[16:17], v[128:129], v[160:161]
	v_pk_mul_f32 v[18:19], v[126:127], v[158:159]
	v_pk_mul_f32 v[8:9], v[16:17], v[8:9]
	v_pk_mul_f32 v[16:17], v[124:125], v[156:157]
	v_pk_mul_f32 v[10:11], v[18:19], v[10:11]
	v_pk_mul_f32 v[18:19], v[122:123], v[154:155]
	v_pk_mul_f32 v[12:13], v[16:17], v[12:13]
	v_mov_b32_e32 v16, 0
	v_pk_mul_f32 v[14:15], v[18:19], v[14:15]
	v_cvt_scalef32_pk_fp8_f32 v16, v10, v11, s96
	v_mov_b32_e32 v17, 0
	v_cvt_scalef32_pk_fp8_f32 v16, v8, v9, s96 op_sel:[0,0,0,1]
	v_cvt_scalef32_pk_fp8_f32 v17, v14, v15, s96
	v_pk_mul_f32 v[8:9], v[152:153], s[26:27] op_sel_hi:[1,0]
	v_cvt_scalef32_pk_fp8_f32 v17, v12, v13, s96 op_sel:[0,0,0,1]
	v_pk_mul_f32 v[10:11], v[150:151], s[26:27] op_sel_hi:[1,0]
	v_pk_mul_f32 v[12:13], v[148:149], s[26:27] op_sel_hi:[1,0]
	v_exp_f32_e32 v8, v8
	v_exp_f32_e32 v9, v9
	v_pk_mul_f32 v[14:15], v[146:147], s[26:27] op_sel_hi:[1,0]
	v_exp_f32_e32 v10, v10
	v_exp_f32_e32 v11, v11
	v_exp_f32_e32 v12, v12
	v_exp_f32_e32 v13, v13
	v_exp_f32_e32 v14, v14
	v_exp_f32_e32 v15, v15
	v_mov_b32_e32 v2, v163
	s_nop 7
	s_nop 7
	s_nop 7
	v_pk_add_f32 v[8:9], v[8:9], 1.0 op_sel_hi:[1,0]
	v_lshl_add_u32 v20, s52, 8, v2
	v_lshl_or_b32 v2, s33, 7, v188
	v_mov_b64_e32 v[4:5], s[12:13]
	v_pk_add_f32 v[10:11], v[10:11], 1.0 op_sel_hi:[1,0]
	v_pk_add_f32 v[12:13], v[12:13], 1.0 op_sel_hi:[1,0]
	v_rcp_f32_e32 v8, v8
	v_rcp_f32_e32 v9, v9
	v_ashrrev_i32_e32 v3, 31, v2
	v_mad_i64_i32 v[6:7], s[8:9], v20, s95, v[4:5]
	v_pk_add_f32 v[14:15], v[14:15], 1.0 op_sel_hi:[1,0]
	v_rcp_f32_e32 v10, v10
	v_rcp_f32_e32 v11, v11
	v_rcp_f32_e32 v12, v12
	v_rcp_f32_e32 v13, v13
	v_lshl_add_u64 v[6:7], v[6:7], 0, v[2:3]
	v_rcp_f32_e32 v14, v14
	v_rcp_f32_e32 v15, v15
	global_store_dwordx2 v[6:7], v[16:17], off nt
	v_pk_mul_f32 v[16:17], v[120:121], v[152:153]
	v_pk_mul_f32 v[18:19], v[118:119], v[150:151]
	v_pk_mul_f32 v[8:9], v[16:17], v[8:9]
	v_pk_mul_f32 v[16:17], v[116:117], v[148:149]
	v_pk_mul_f32 v[10:11], v[18:19], v[10:11]
	v_pk_mul_f32 v[18:19], v[114:115], v[146:147]
	v_pk_mul_f32 v[12:13], v[16:17], v[12:13]
	v_mov_b32_e32 v16, 0
	v_pk_mul_f32 v[14:15], v[18:19], v[14:15]
	v_cvt_scalef32_pk_fp8_f32 v16, v10, v11, s96
	v_mov_b32_e32 v17, 0
	v_cvt_scalef32_pk_fp8_f32 v16, v8, v9, s96 op_sel:[0,0,0,1]
	v_cvt_scalef32_pk_fp8_f32 v17, v14, v15, s96
	v_pk_mul_f32 v[8:9], v[144:145], s[26:27] op_sel_hi:[1,0]
	v_cvt_scalef32_pk_fp8_f32 v17, v12, v13, s96 op_sel:[0,0,0,1]
	v_pk_mul_f32 v[10:11], v[142:143], s[26:27] op_sel_hi:[1,0]
	v_pk_mul_f32 v[12:13], v[140:141], s[26:27] op_sel_hi:[1,0]
	v_exp_f32_e32 v8, v8
	v_exp_f32_e32 v9, v9
	v_pk_mul_f32 v[14:15], v[138:139], s[26:27] op_sel_hi:[1,0]
	v_exp_f32_e32 v10, v10
	v_exp_f32_e32 v11, v11
	v_exp_f32_e32 v12, v12
	v_exp_f32_e32 v13, v13
	v_exp_f32_e32 v14, v14
	v_exp_f32_e32 v15, v15
	v_pk_add_f32 v[8:9], v[8:9], 1.0 op_sel_hi:[1,0]
	v_add_u32_e32 v6, 16, v20
	v_pk_add_f32 v[10:11], v[10:11], 1.0 op_sel_hi:[1,0]
	v_pk_add_f32 v[12:13], v[12:13], 1.0 op_sel_hi:[1,0]
	v_rcp_f32_e32 v8, v8
	v_rcp_f32_e32 v9, v9
	v_mad_i64_i32 v[6:7], s[8:9], v6, s95, v[4:5]
	v_pk_add_f32 v[14:15], v[14:15], 1.0 op_sel_hi:[1,0]
	v_rcp_f32_e32 v10, v10
	v_rcp_f32_e32 v11, v11
	v_rcp_f32_e32 v12, v12
	v_rcp_f32_e32 v13, v13
	v_lshl_add_u64 v[6:7], v[6:7], 0, v[2:3]
	v_rcp_f32_e32 v14, v14
	v_rcp_f32_e32 v15, v15
	global_store_dwordx2 v[6:7], v[16:17], off nt
	v_pk_mul_f32 v[16:17], v[112:113], v[144:145]
	v_pk_mul_f32 v[18:19], v[110:111], v[142:143]
	v_pk_mul_f32 v[8:9], v[16:17], v[8:9]
	v_pk_mul_f32 v[16:17], v[108:109], v[140:141]
	v_pk_mul_f32 v[10:11], v[18:19], v[10:11]
	v_pk_mul_f32 v[18:19], v[106:107], v[138:139]
	v_pk_mul_f32 v[12:13], v[16:17], v[12:13]
	v_mov_b32_e32 v16, 0
	v_pk_mul_f32 v[14:15], v[18:19], v[14:15]
	v_cvt_scalef32_pk_fp8_f32 v16, v10, v11, s96
	v_mov_b32_e32 v17, 0
	v_cvt_scalef32_pk_fp8_f32 v16, v8, v9, s96 op_sel:[0,0,0,1]
	v_cvt_scalef32_pk_fp8_f32 v17, v14, v15, s96
	v_pk_mul_f32 v[8:9], v[136:137], s[26:27] op_sel_hi:[1,0]
	v_cvt_scalef32_pk_fp8_f32 v17, v12, v13, s96 op_sel:[0,0,0,1]
	v_pk_mul_f32 v[10:11], v[134:135], s[26:27] op_sel_hi:[1,0]
	v_pk_mul_f32 v[12:13], v[132:133], s[26:27] op_sel_hi:[1,0]
	v_exp_f32_e32 v8, v8
	v_exp_f32_e32 v9, v9
	v_pk_mul_f32 v[14:15], v[130:131], s[26:27] op_sel_hi:[1,0]
	v_exp_f32_e32 v10, v10
	v_exp_f32_e32 v11, v11
	v_exp_f32_e32 v12, v12
	v_exp_f32_e32 v13, v13
	v_exp_f32_e32 v14, v14
	v_exp_f32_e32 v15, v15
	v_pk_add_f32 v[8:9], v[8:9], 1.0 op_sel_hi:[1,0]
	v_add_u32_e32 v6, 32, v20
	v_pk_add_f32 v[10:11], v[10:11], 1.0 op_sel_hi:[1,0]
	v_pk_add_f32 v[12:13], v[12:13], 1.0 op_sel_hi:[1,0]
	v_rcp_f32_e32 v8, v8
	v_rcp_f32_e32 v9, v9
	v_mad_i64_i32 v[6:7], s[8:9], v6, s95, v[4:5]
	v_pk_add_f32 v[14:15], v[14:15], 1.0 op_sel_hi:[1,0]
	v_rcp_f32_e32 v10, v10
	v_rcp_f32_e32 v11, v11
	v_rcp_f32_e32 v12, v12
	v_rcp_f32_e32 v13, v13
	v_lshl_add_u64 v[6:7], v[6:7], 0, v[2:3]
	v_rcp_f32_e32 v14, v14
	v_rcp_f32_e32 v15, v15
	global_store_dwordx2 v[6:7], v[16:17], off nt
	v_pk_mul_f32 v[16:17], v[104:105], v[136:137]
	v_pk_mul_f32 v[18:19], v[102:103], v[134:135]
	v_pk_mul_f32 v[8:9], v[16:17], v[8:9]
	v_pk_mul_f32 v[16:17], v[100:101], v[132:133]
	v_pk_mul_f32 v[10:11], v[18:19], v[10:11]
	v_pk_mul_f32 v[18:19], v[98:99], v[130:131]
	v_pk_mul_f32 v[12:13], v[16:17], v[12:13]
	v_mov_b32_e32 v16, 0
	v_pk_mul_f32 v[14:15], v[18:19], v[14:15]
	v_cvt_scalef32_pk_fp8_f32 v16, v10, v11, s96
	v_mov_b32_e32 v17, 0
	v_cvt_scalef32_pk_fp8_f32 v16, v8, v9, s96 op_sel:[0,0,0,1]
	v_cvt_scalef32_pk_fp8_f32 v17, v14, v15, s96
	v_pk_mul_f32 v[8:9], v[96:97], s[26:27] op_sel_hi:[1,0]
	v_cvt_scalef32_pk_fp8_f32 v17, v12, v13, s96 op_sel:[0,0,0,1]
	v_pk_mul_f32 v[10:11], v[94:95], s[26:27] op_sel_hi:[1,0]
	v_pk_mul_f32 v[12:13], v[92:93], s[26:27] op_sel_hi:[1,0]
	v_exp_f32_e32 v8, v8
	v_exp_f32_e32 v9, v9
	v_pk_mul_f32 v[14:15], v[90:91], s[26:27] op_sel_hi:[1,0]
	v_exp_f32_e32 v10, v10
	v_exp_f32_e32 v11, v11
	v_exp_f32_e32 v12, v12
	v_exp_f32_e32 v13, v13
	v_exp_f32_e32 v14, v14
	v_exp_f32_e32 v15, v15
	v_pk_add_f32 v[8:9], v[8:9], 1.0 op_sel_hi:[1,0]
	v_add_u32_e32 v6, 48, v20
	v_pk_add_f32 v[10:11], v[10:11], 1.0 op_sel_hi:[1,0]
	v_pk_add_f32 v[12:13], v[12:13], 1.0 op_sel_hi:[1,0]
	v_rcp_f32_e32 v8, v8
	v_rcp_f32_e32 v9, v9
	v_mad_i64_i32 v[6:7], s[8:9], v6, s95, v[4:5]
	v_pk_add_f32 v[14:15], v[14:15], 1.0 op_sel_hi:[1,0]
	v_rcp_f32_e32 v10, v10
	v_rcp_f32_e32 v11, v11
	v_rcp_f32_e32 v12, v12
	v_rcp_f32_e32 v13, v13
	v_lshl_add_u64 v[6:7], v[6:7], 0, v[2:3]
	v_rcp_f32_e32 v14, v14
	v_rcp_f32_e32 v15, v15
	global_store_dwordx2 v[6:7], v[16:17], off nt
	v_pk_mul_f32 v[16:17], v[64:65], v[96:97]
	v_pk_mul_f32 v[18:19], v[62:63], v[94:95]
	v_pk_mul_f32 v[8:9], v[16:17], v[8:9]
	v_pk_mul_f32 v[16:17], v[60:61], v[92:93]
	v_pk_mul_f32 v[10:11], v[18:19], v[10:11]
	v_pk_mul_f32 v[18:19], v[58:59], v[90:91]
	v_pk_mul_f32 v[12:13], v[16:17], v[12:13]
	v_mov_b32_e32 v16, 0
	v_pk_mul_f32 v[14:15], v[18:19], v[14:15]
	v_cvt_scalef32_pk_fp8_f32 v16, v10, v11, s96
	v_mov_b32_e32 v17, 0
	v_cvt_scalef32_pk_fp8_f32 v16, v8, v9, s96 op_sel:[0,0,0,1]
	v_cvt_scalef32_pk_fp8_f32 v17, v14, v15, s96
	v_pk_mul_f32 v[8:9], v[88:89], s[26:27] op_sel_hi:[1,0]
	v_cvt_scalef32_pk_fp8_f32 v17, v12, v13, s96 op_sel:[0,0,0,1]
	v_pk_mul_f32 v[10:11], v[86:87], s[26:27] op_sel_hi:[1,0]
	v_pk_mul_f32 v[12:13], v[84:85], s[26:27] op_sel_hi:[1,0]
	v_exp_f32_e32 v8, v8
	v_exp_f32_e32 v9, v9
	v_pk_mul_f32 v[14:15], v[82:83], s[26:27] op_sel_hi:[1,0]
	v_exp_f32_e32 v10, v10
	v_exp_f32_e32 v11, v11
	v_exp_f32_e32 v12, v12
	v_exp_f32_e32 v13, v13
	v_exp_f32_e32 v14, v14
	v_exp_f32_e32 v15, v15
	v_pk_add_f32 v[8:9], v[8:9], 1.0 op_sel_hi:[1,0]
	v_add_u32_e32 v6, 0x80, v20
	v_pk_add_f32 v[10:11], v[10:11], 1.0 op_sel_hi:[1,0]
	v_pk_add_f32 v[12:13], v[12:13], 1.0 op_sel_hi:[1,0]
	v_rcp_f32_e32 v8, v8
	v_rcp_f32_e32 v9, v9
	v_mad_i64_i32 v[6:7], s[8:9], v6, s95, v[4:5]
	v_pk_add_f32 v[14:15], v[14:15], 1.0 op_sel_hi:[1,0]
	v_rcp_f32_e32 v10, v10
	v_rcp_f32_e32 v11, v11
	v_rcp_f32_e32 v12, v12
	v_rcp_f32_e32 v13, v13
	v_lshl_add_u64 v[6:7], v[6:7], 0, v[2:3]
	v_rcp_f32_e32 v14, v14
	v_rcp_f32_e32 v15, v15
	global_store_dwordx2 v[6:7], v[16:17], off nt
	v_pk_mul_f32 v[16:17], v[56:57], v[88:89]
	v_pk_mul_f32 v[18:19], v[54:55], v[86:87]
	v_pk_mul_f32 v[8:9], v[16:17], v[8:9]
	v_pk_mul_f32 v[16:17], v[52:53], v[84:85]
	v_pk_mul_f32 v[10:11], v[18:19], v[10:11]
	v_pk_mul_f32 v[18:19], v[50:51], v[82:83]
	v_pk_mul_f32 v[12:13], v[16:17], v[12:13]
	v_mov_b32_e32 v16, 0
	v_pk_mul_f32 v[14:15], v[18:19], v[14:15]
	v_cvt_scalef32_pk_fp8_f32 v16, v10, v11, s96
	v_mov_b32_e32 v17, 0
	v_cvt_scalef32_pk_fp8_f32 v16, v8, v9, s96 op_sel:[0,0,0,1]
	v_cvt_scalef32_pk_fp8_f32 v17, v14, v15, s96
	v_pk_mul_f32 v[8:9], v[80:81], s[26:27] op_sel_hi:[1,0]
	v_pk_mul_f32 v[10:11], v[78:79], s[26:27] op_sel_hi:[1,0]
	v_cvt_scalef32_pk_fp8_f32 v17, v12, v13, s96 op_sel:[0,0,0,1]
	v_pk_mul_f32 v[12:13], v[76:77], s[26:27] op_sel_hi:[1,0]
	v_pk_mul_f32 v[14:15], v[74:75], s[26:27] op_sel_hi:[1,0]
	v_exp_f32_e32 v10, v10
	v_exp_f32_e32 v11, v11
	v_exp_f32_e32 v8, v8
	v_exp_f32_e32 v9, v9
	v_exp_f32_e32 v14, v14
	v_exp_f32_e32 v12, v12
	v_exp_f32_e32 v13, v13
	v_exp_f32_e32 v15, v15
	v_pk_add_f32 v[8:9], v[8:9], 1.0 op_sel_hi:[1,0]
	v_pk_add_f32 v[10:11], v[10:11], 1.0 op_sel_hi:[1,0]
	v_add_u32_e32 v6, 0x90, v20
	v_pk_add_f32 v[12:13], v[12:13], 1.0 op_sel_hi:[1,0]
	v_pk_add_f32 v[14:15], v[14:15], 1.0 op_sel_hi:[1,0]
	v_rcp_f32_e32 v10, v10
	v_rcp_f32_e32 v11, v11
	v_rcp_f32_e32 v8, v8
	v_rcp_f32_e32 v9, v9
	v_mad_i64_i32 v[6:7], s[8:9], v6, s95, v[4:5]
	v_rcp_f32_e32 v14, v14
	v_rcp_f32_e32 v15, v15
	v_rcp_f32_e32 v12, v12
	v_rcp_f32_e32 v13, v13
	v_lshl_add_u64 v[6:7], v[6:7], 0, v[2:3]
	global_store_dwordx2 v[6:7], v[16:17], off nt
	v_pk_mul_f32 v[16:17], v[48:49], v[80:81]
	v_pk_mul_f32 v[18:19], v[46:47], v[78:79]
	v_pk_mul_f32 v[8:9], v[16:17], v[8:9]
	v_pk_mul_f32 v[10:11], v[18:19], v[10:11]
	v_pk_mul_f32 v[16:17], v[44:45], v[76:77]
	v_pk_mul_f32 v[18:19], v[42:43], v[74:75]
	v_add_u32_e32 v6, 0xa0, v20
	v_pk_mul_f32 v[12:13], v[16:17], v[12:13]
	v_pk_mul_f32 v[14:15], v[18:19], v[14:15]
	v_mov_b32_e32 v16, 0
	v_mov_b32_e32 v17, 0
	v_mad_i64_i32 v[6:7], s[8:9], v6, s95, v[4:5]
	v_cvt_scalef32_pk_fp8_f32 v16, v10, v11, s96
	v_cvt_scalef32_pk_fp8_f32 v17, v14, v15, s96
	v_lshl_add_u64 v[6:7], v[6:7], 0, v[2:3]
	v_cvt_scalef32_pk_fp8_f32 v16, v8, v9, s96 op_sel:[0,0,0,1]
	v_cvt_scalef32_pk_fp8_f32 v17, v12, v13, s96 op_sel:[0,0,0,1]
	global_store_dwordx2 v[6:7], v[16:17], off nt
	v_add_u32_e32 v6, 0xb0, v20
	v_mad_i64_i32 v[4:5], s[8:9], v6, s95, v[4:5]
	v_pk_mul_f32 v[6:7], v[72:73], s[26:27] op_sel_hi:[1,0]
	v_pk_mul_f32 v[8:9], v[70:71], s[26:27] op_sel_hi:[1,0]
	v_pk_mul_f32 v[10:11], v[68:69], s[26:27] op_sel_hi:[1,0]
	v_pk_mul_f32 v[12:13], v[66:67], s[26:27] op_sel_hi:[1,0]
	v_exp_f32_e32 v8, v8
	v_exp_f32_e32 v9, v9
	v_exp_f32_e32 v6, v6
	v_exp_f32_e32 v7, v7
	v_exp_f32_e32 v12, v12
	v_exp_f32_e32 v10, v10
	v_exp_f32_e32 v11, v11
	v_exp_f32_e32 v13, v13
	v_pk_add_f32 v[6:7], v[6:7], 1.0 op_sel_hi:[1,0]
	v_pk_add_f32 v[8:9], v[8:9], 1.0 op_sel_hi:[1,0]
	v_pk_add_f32 v[10:11], v[10:11], 1.0 op_sel_hi:[1,0]
	v_pk_add_f32 v[12:13], v[12:13], 1.0 op_sel_hi:[1,0]
	v_rcp_f32_e32 v8, v8
	v_rcp_f32_e32 v9, v9
	v_rcp_f32_e32 v6, v6
	v_rcp_f32_e32 v7, v7
	v_rcp_f32_e32 v12, v12
	v_rcp_f32_e32 v13, v13
	v_rcp_f32_e32 v10, v10
	v_rcp_f32_e32 v11, v11
	v_lshl_add_u64 v[2:3], v[4:5], 0, v[2:3]
	v_pk_mul_f32 v[4:5], v[40:41], v[72:73]
	v_pk_mul_f32 v[14:15], v[38:39], v[70:71]
	v_pk_mul_f32 v[4:5], v[4:5], v[6:7]
	v_pk_mul_f32 v[6:7], v[14:15], v[8:9]
	v_pk_mul_f32 v[8:9], v[36:37], v[68:69]
	v_pk_mul_f32 v[14:15], v[34:35], v[66:67]
	v_pk_mul_f32 v[8:9], v[8:9], v[10:11]
	v_pk_mul_f32 v[10:11], v[14:15], v[12:13]
	v_mov_b32_e32 v12, 0
	v_mov_b32_e32 v13, 0
	v_cvt_scalef32_pk_fp8_f32 v12, v6, v7, s96
	v_cvt_scalef32_pk_fp8_f32 v13, v10, v11, s96
	v_cvt_scalef32_pk_fp8_f32 v12, v4, v5, s96 op_sel:[0,0,0,1]
	v_cvt_scalef32_pk_fp8_f32 v13, v8, v9, s96 op_sel:[0,0,0,1]
	s_andn2_b64 vcc, exec, s[2:3]
	s_mov_b64 s[2:3], -1
	global_store_dwordx2 v[2:3], v[12:13], off nt
	s_cbranch_vccnz .LBB0_194
	s_andn2_b64 vcc, exec, s[0:1]
	s_cbranch_vccnz .LBB0_193
	s_barrier
	s_branch .LBB0_193

.LBB0_289:
	v_mov_b32_e32 v2, v184
	s_cmp_eq_u32 s93, 0
	s_nop 7
	s_nop 7
	s_nop 7
	s_cselect_b64 vcc, -1, 0
	v_add_u32_e32 v3, 0xffffe000, v2
	v_cndmask_b32_e32 v2, v3, v2, vcc
	v_lshl_add_u32 v2, s70, 8, v2
	s_and_b64 s[8:9], vcc, exec
	v_ashrrev_i32_e32 v3, 31, v2
	s_cselect_b32 s9, s21, s17
	s_cselect_b32 s8, s20, s16
	v_lshlrev_b64 v[2:3], 13, v[2:3]
	s_waitcnt vmcnt(0)
	v_pk_mul_f32 v[180:181], v[142:143], s[46:47] op_sel_hi:[1,0]
	v_lshl_add_u64 v[2:3], s[8:9], 0, v[2:3]
	v_pk_mul_f32 v[176:177], v[138:139], s[46:47] op_sel_hi:[1,0]
	v_pk_mul_f32 v[178:179], v[144:145], s[46:47] op_sel_hi:[1,0]
	v_pk_mul_f32 v[190:191], v[134:135], v[180:181]
	v_lshl_add_u64 v[6:7], v[172:173], 1, v[2:3]
	v_pk_mul_f32 v[172:173], v[150:151], s[46:47] op_sel_hi:[1,0]
	v_pk_mul_f32 v[174:175], v[140:141], s[46:47] op_sel_hi:[1,0]
	v_pk_mul_f32 v[182:183], v[136:137], v[178:179]
	v_pk_mul_f32 v[192:193], v[130:131], v[176:177]
	v_cvt_pk_bf16_f32 v190, v190, v191
	v_cvt_pk_bf16_f32 v191, v182, v183
	v_pk_mul_f32 v[4:5], v[146:147], s[46:47] op_sel_hi:[1,0]
	v_pk_mul_f32 v[8:9], v[152:153], s[46:47] op_sel_hi:[1,0]
	v_pk_mul_f32 v[194:195], v[132:133], v[174:175]
	v_cvt_pk_bf16_f32 v192, v192, v193
	v_pk_mul_f32 v[2:3], v[148:149], s[46:47] op_sel_hi:[1,0]
	v_cvt_pk_bf16_f32 v193, v194, v195
	global_store_dwordx4 v[6:7], v[190:193], off nt
	v_pk_mul_f32 v[182:183], v[104:105], v[8:9]
	v_pk_mul_f32 v[194:195], v[100:101], v[2:3]
	v_pk_mul_f32 v[190:191], v[102:103], v[172:173]
	v_pk_mul_f32 v[192:193], v[98:99], v[4:5]
	v_cvt_pk_bf16_f32 v190, v190, v191
	v_cvt_pk_bf16_f32 v191, v182, v183
	v_pk_mul_f32 v[182:183], v[128:129], v[178:179]
	v_cvt_pk_bf16_f32 v192, v192, v193
	v_cvt_pk_bf16_f32 v193, v194, v195
	global_store_dwordx4 v[6:7], v[190:193], off offset:256
	s_mov_b32 s8, 0x20000
	v_pk_mul_f32 v[194:195], v[124:125], v[174:175]
	v_pk_mul_f32 v[190:191], v[126:127], v[180:181]
	v_pk_mul_f32 v[192:193], v[122:123], v[176:177]
	v_cvt_pk_bf16_f32 v190, v190, v191
	v_cvt_pk_bf16_f32 v191, v182, v183
	v_add_co_u32_e32 v182, vcc, s8, v6
	v_cvt_pk_bf16_f32 v192, v192, v193
	v_cvt_pk_bf16_f32 v193, v194, v195
	v_pk_mul_f32 v[194:195], v[92:93], v[2:3]
	s_nop 0
	v_addc_co_u32_e32 v183, vcc, 0, v7, vcc
	global_store_dwordx4 v[182:183], v[190:193], off nt
	v_pk_mul_f32 v[196:197], v[90:91], v[4:5]
	s_mov_b32 s8, 0x40000
	v_pk_mul_f32 v[190:191], v[94:95], v[172:173]
	v_pk_mul_f32 v[192:193], v[96:97], v[8:9]
	v_cvt_pk_bf16_f32 v190, v190, v191
	s_nop 0
	v_cvt_pk_bf16_f32 v191, v192, v193
	v_cvt_pk_bf16_f32 v192, v196, v197
	v_cvt_pk_bf16_f32 v193, v194, v195
	global_store_dwordx4 v[182:183], v[190:193], off offset:256
	v_pk_mul_f32 v[182:183], v[120:121], v[178:179]
	v_pk_mul_f32 v[194:195], v[116:117], v[174:175]
	v_pk_mul_f32 v[190:191], v[118:119], v[180:181]
	v_pk_mul_f32 v[192:193], v[114:115], v[176:177]
	v_cvt_pk_bf16_f32 v190, v190, v191
	v_cvt_pk_bf16_f32 v191, v182, v183
	v_add_co_u32_e32 v182, vcc, s8, v6
	v_cvt_pk_bf16_f32 v192, v192, v193
	v_cvt_pk_bf16_f32 v193, v194, v195
	v_pk_mul_f32 v[194:195], v[84:85], v[2:3]
	s_nop 0
	v_addc_co_u32_e32 v183, vcc, 0, v7, vcc
	global_store_dwordx4 v[182:183], v[190:193], off nt
	v_pk_mul_f32 v[196:197], v[82:83], v[4:5]
	s_mov_b32 s8, 0x60000
	v_pk_mul_f32 v[190:191], v[86:87], v[172:173]
	v_pk_mul_f32 v[192:193], v[88:89], v[8:9]
	v_cvt_pk_bf16_f32 v190, v190, v191
	s_nop 0
	v_cvt_pk_bf16_f32 v191, v192, v193
	v_cvt_pk_bf16_f32 v192, v196, v197
	v_cvt_pk_bf16_f32 v193, v194, v195
	global_store_dwordx4 v[182:183], v[190:193], off offset:256
	v_pk_mul_f32 v[182:183], v[112:113], v[178:179]
	v_pk_mul_f32 v[194:195], v[108:109], v[174:175]
	v_pk_mul_f32 v[190:191], v[110:111], v[180:181]
	v_pk_mul_f32 v[192:193], v[106:107], v[176:177]
	v_cvt_pk_bf16_f32 v190, v190, v191
	v_cvt_pk_bf16_f32 v191, v182, v183
	v_add_co_u32_e32 v182, vcc, s8, v6
	v_cvt_pk_bf16_f32 v192, v192, v193
	v_cvt_pk_bf16_f32 v193, v194, v195
	v_pk_mul_f32 v[194:195], v[76:77], v[2:3]
	s_nop 0
	v_addc_co_u32_e32 v183, vcc, 0, v7, vcc
	global_store_dwordx4 v[182:183], v[190:193], off nt
	v_pk_mul_f32 v[196:197], v[74:75], v[4:5]
	s_mov_b32 s8, 0x100000
	v_pk_mul_f32 v[190:191], v[78:79], v[172:173]
	v_pk_mul_f32 v[192:193], v[80:81], v[8:9]
	v_cvt_pk_bf16_f32 v190, v190, v191
	s_nop 0
	v_cvt_pk_bf16_f32 v191, v192, v193
	v_cvt_pk_bf16_f32 v192, v196, v197
	v_cvt_pk_bf16_f32 v193, v194, v195
	global_store_dwordx4 v[182:183], v[190:193], off offset:256
	v_pk_mul_f32 v[182:183], v[72:73], v[178:179]
	v_pk_mul_f32 v[194:195], v[68:69], v[174:175]
	v_pk_mul_f32 v[190:191], v[70:71], v[180:181]
	v_pk_mul_f32 v[192:193], v[66:67], v[176:177]
	v_cvt_pk_bf16_f32 v190, v190, v191
	v_cvt_pk_bf16_f32 v191, v182, v183
	v_add_co_u32_e32 v182, vcc, s8, v6
	v_cvt_pk_bf16_f32 v192, v192, v193
	v_cvt_pk_bf16_f32 v193, v194, v195
	v_pk_mul_f32 v[194:195], v[36:37], v[2:3]
	s_nop 0
	v_addc_co_u32_e32 v183, vcc, 0, v7, vcc
	global_store_dwordx4 v[182:183], v[190:193], off nt
	v_pk_mul_f32 v[196:197], v[34:35], v[4:5]
	s_mov_b32 s8, 0x120000
	v_pk_mul_f32 v[190:191], v[38:39], v[172:173]
	v_pk_mul_f32 v[192:193], v[40:41], v[8:9]
	v_cvt_pk_bf16_f32 v190, v190, v191
	s_nop 0
	v_cvt_pk_bf16_f32 v191, v192, v193
	v_cvt_pk_bf16_f32 v192, v196, v197
	v_cvt_pk_bf16_f32 v193, v194, v195
	global_store_dwordx4 v[182:183], v[190:193], off offset:256
	v_pk_mul_f32 v[182:183], v[64:65], v[178:179]
	v_pk_mul_f32 v[194:195], v[60:61], v[174:175]
	v_pk_mul_f32 v[190:191], v[62:63], v[180:181]
	v_pk_mul_f32 v[192:193], v[58:59], v[176:177]
	v_cvt_pk_bf16_f32 v190, v190, v191
	v_cvt_pk_bf16_f32 v191, v182, v183
	v_add_co_u32_e32 v182, vcc, s8, v6
	v_cvt_pk_bf16_f32 v192, v192, v193
	v_cvt_pk_bf16_f32 v193, v194, v195
	v_pk_mul_f32 v[194:195], v[28:29], v[2:3]
	s_nop 0
	v_addc_co_u32_e32 v183, vcc, 0, v7, vcc
	global_store_dwordx4 v[182:183], v[190:193], off nt
	v_pk_mul_f32 v[196:197], v[26:27], v[4:5]
	s_mov_b32 s8, 0x140000
	v_pk_mul_f32 v[190:191], v[30:31], v[172:173]
	v_pk_mul_f32 v[192:193], v[32:33], v[8:9]
	v_cvt_pk_bf16_f32 v190, v190, v191
	s_nop 0
	v_cvt_pk_bf16_f32 v191, v192, v193
	v_cvt_pk_bf16_f32 v192, v196, v197
	v_cvt_pk_bf16_f32 v193, v194, v195
	global_store_dwordx4 v[182:183], v[190:193], off offset:256
	v_pk_mul_f32 v[182:183], v[56:57], v[178:179]
	v_pk_mul_f32 v[194:195], v[52:53], v[174:175]
	v_pk_mul_f32 v[190:191], v[54:55], v[180:181]
	v_pk_mul_f32 v[192:193], v[50:51], v[176:177]
	v_cvt_pk_bf16_f32 v190, v190, v191
	v_cvt_pk_bf16_f32 v191, v182, v183
	v_add_co_u32_e32 v182, vcc, s8, v6
	s_mov_b32 s8, 0x160000
	s_nop 0
	v_addc_co_u32_e32 v183, vcc, 0, v7, vcc
	v_cvt_pk_bf16_f32 v192, v192, v193
	v_cvt_pk_bf16_f32 v193, v194, v195
	v_add_co_u32_e32 v6, vcc, s8, v6
	global_store_dwordx4 v[182:183], v[190:193], off nt
	s_nop 0
	v_addc_co_u32_e32 v7, vcc, 0, v7, vcc
	v_pk_mul_f32 v[192:193], v[24:25], v[8:9]
	v_pk_mul_f32 v[190:191], v[22:23], v[172:173]
	v_pk_mul_f32 v[194:195], v[20:21], v[2:3]
	v_pk_mul_f32 v[196:197], v[18:19], v[4:5]
	v_cvt_pk_bf16_f32 v190, v190, v191
	v_cvt_pk_bf16_f32 v191, v192, v193
	v_pk_mul_f32 v[178:179], v[48:49], v[178:179]
	v_cvt_pk_bf16_f32 v192, v196, v197
	v_cvt_pk_bf16_f32 v193, v194, v195
	global_store_dwordx4 v[182:183], v[190:193], off offset:256
	v_pk_mul_f32 v[180:181], v[46:47], v[180:181]
	v_pk_mul_f32 v[182:183], v[44:45], v[174:175]
	v_pk_mul_f32 v[176:177], v[42:43], v[176:177]
	v_cvt_pk_bf16_f32 v174, v180, v181
	v_cvt_pk_bf16_f32 v175, v178, v179
	v_pk_mul_f32 v[4:5], v[10:11], v[4:5]
	s_and_b64 vcc, exec, s[2:3]
	s_mov_b64 s[2:3], -1
	v_cvt_pk_bf16_f32 v176, v176, v177
	v_cvt_pk_bf16_f32 v177, v182, v183
	global_store_dwordx4 v[6:7], v[174:177], off nt
	v_pk_mul_f32 v[8:9], v[16:17], v[8:9]
	v_pk_mul_f32 v[172:173], v[14:15], v[172:173]
	v_pk_mul_f32 v[174:175], v[12:13], v[2:3]
	v_cvt_pk_bf16_f32 v2, v172, v173
	v_cvt_pk_bf16_f32 v3, v8, v9
	v_cvt_pk_bf16_f32 v4, v4, v5
	s_nop 0
	v_cvt_pk_bf16_f32 v5, v174, v175
	global_store_dwordx4 v[6:7], v[2:5], off offset:256
	s_cbranch_vccnz .LBB0_269
	s_andn2_b64 vcc, exec, s[6:7]
	s_cbranch_vccnz .LBB0_268
	s_barrier
	s_branch .LBB0_268

.LBB0_441:
	v_lshl_or_b32 v4, s70, 8, v198
	v_ashrrev_i32_e32 v5, 31, v4
	v_lshl_add_u32 v16, s52, 8, v197
	v_mov_b64_e32 v[2:3], s[16:17]
	v_mad_i64_i32 v[6:7], s[8:9], v16, s95, v[2:3]
	v_lshlrev_b64 v[4:5], 1, v[4:5]
	v_lshl_add_u64 v[10:11], v[6:7], 0, v[4:5]
	v_pk_mul_f32 v[6:7], v[158:159], s[38:39] op_sel_hi:[1,0]
	s_nop 7
	s_nop 7
	s_nop 7
	v_pk_mul_f32 v[8:9], v[160:161], s[38:39] op_sel_hi:[1,0]
	v_cvt_pk_bf16_f32 v6, v6, v7
	v_pk_mul_f32 v[12:13], v[156:157], s[38:39] op_sel_hi:[1,0]
	v_cvt_pk_bf16_f32 v7, v8, v9
	v_pk_mul_f32 v[14:15], v[154:155], s[38:39] op_sel_hi:[1,0]
	s_andn2_b64 vcc, exec, s[2:3]
	v_cvt_pk_bf16_f32 v8, v14, v15
	v_cvt_pk_bf16_f32 v9, v12, v13
	global_store_dwordx4 v[10:11], v[6:9], off nt
	v_pk_mul_f32 v[12:13], v[124:125], s[38:39] op_sel_hi:[1,0]
	v_pk_mul_f32 v[14:15], v[122:123], s[38:39] op_sel_hi:[1,0]
	v_pk_mul_f32 v[6:7], v[126:127], s[38:39] op_sel_hi:[1,0]
	v_pk_mul_f32 v[8:9], v[128:129], s[38:39] op_sel_hi:[1,0]
	v_cvt_pk_bf16_f32 v6, v6, v7
	s_mov_b64 s[2:3], -1
	v_cvt_pk_bf16_f32 v7, v8, v9
	v_cvt_pk_bf16_f32 v8, v14, v15
	v_cvt_pk_bf16_f32 v9, v12, v13
	global_store_dwordx4 v[10:11], v[6:9], off offset:256
	v_pk_mul_f32 v[12:13], v[148:149], s[38:39] op_sel_hi:[1,0]
	v_pk_mul_f32 v[14:15], v[146:147], s[38:39] op_sel_hi:[1,0]
	v_or_b32_e32 v6, 16, v16
	v_mad_i64_i32 v[6:7], s[8:9], v6, s95, v[2:3]
	v_lshl_add_u64 v[10:11], v[6:7], 0, v[4:5]
	v_pk_mul_f32 v[6:7], v[150:151], s[38:39] op_sel_hi:[1,0]
	v_pk_mul_f32 v[8:9], v[152:153], s[38:39] op_sel_hi:[1,0]
	v_cvt_pk_bf16_f32 v6, v6, v7
	s_nop 0
	v_cvt_pk_bf16_f32 v7, v8, v9
	v_cvt_pk_bf16_f32 v8, v14, v15
	v_cvt_pk_bf16_f32 v9, v12, v13
	global_store_dwordx4 v[10:11], v[6:9], off nt
	v_pk_mul_f32 v[12:13], v[116:117], s[38:39] op_sel_hi:[1,0]
	v_pk_mul_f32 v[14:15], v[114:115], s[38:39] op_sel_hi:[1,0]
	v_pk_mul_f32 v[6:7], v[118:119], s[38:39] op_sel_hi:[1,0]
	v_pk_mul_f32 v[8:9], v[120:121], s[38:39] op_sel_hi:[1,0]
	v_cvt_pk_bf16_f32 v6, v6, v7
	s_nop 0
	v_cvt_pk_bf16_f32 v7, v8, v9
	v_cvt_pk_bf16_f32 v8, v14, v15
	v_cvt_pk_bf16_f32 v9, v12, v13
	global_store_dwordx4 v[10:11], v[6:9], off offset:256
	v_pk_mul_f32 v[12:13], v[140:141], s[38:39] op_sel_hi:[1,0]
	v_pk_mul_f32 v[14:15], v[138:139], s[38:39] op_sel_hi:[1,0]
	v_or_b32_e32 v6, 32, v16
	v_mad_i64_i32 v[6:7], s[8:9], v6, s95, v[2:3]
	v_lshl_add_u64 v[10:11], v[6:7], 0, v[4:5]
	v_pk_mul_f32 v[6:7], v[142:143], s[38:39] op_sel_hi:[1,0]
	v_pk_mul_f32 v[8:9], v[144:145], s[38:39] op_sel_hi:[1,0]
	v_cvt_pk_bf16_f32 v6, v6, v7
	s_nop 0
	v_cvt_pk_bf16_f32 v7, v8, v9
	v_cvt_pk_bf16_f32 v8, v14, v15
	v_cvt_pk_bf16_f32 v9, v12, v13
	global_store_dwordx4 v[10:11], v[6:9], off nt
	v_pk_mul_f32 v[12:13], v[108:109], s[38:39] op_sel_hi:[1,0]
	v_pk_mul_f32 v[14:15], v[106:107], s[38:39] op_sel_hi:[1,0]
	v_pk_mul_f32 v[6:7], v[110:111], s[38:39] op_sel_hi:[1,0]
	v_pk_mul_f32 v[8:9], v[112:113], s[38:39] op_sel_hi:[1,0]
	v_cvt_pk_bf16_f32 v6, v6, v7
	s_nop 0
	v_cvt_pk_bf16_f32 v7, v8, v9
	v_cvt_pk_bf16_f32 v8, v14, v15
	v_cvt_pk_bf16_f32 v9, v12, v13
	global_store_dwordx4 v[10:11], v[6:9], off offset:256
	v_pk_mul_f32 v[12:13], v[132:133], s[38:39] op_sel_hi:[1,0]
	v_pk_mul_f32 v[14:15], v[130:131], s[38:39] op_sel_hi:[1,0]
	v_or_b32_e32 v6, 48, v16
	v_mad_i64_i32 v[6:7], s[8:9], v6, s95, v[2:3]
	v_lshl_add_u64 v[10:11], v[6:7], 0, v[4:5]
	v_pk_mul_f32 v[6:7], v[134:135], s[38:39] op_sel_hi:[1,0]
	v_pk_mul_f32 v[8:9], v[136:137], s[38:39] op_sel_hi:[1,0]
	v_cvt_pk_bf16_f32 v6, v6, v7
	s_nop 0
	v_cvt_pk_bf16_f32 v7, v8, v9
	v_cvt_pk_bf16_f32 v8, v14, v15
	v_cvt_pk_bf16_f32 v9, v12, v13
	global_store_dwordx4 v[10:11], v[6:9], off nt
	v_pk_mul_f32 v[12:13], v[100:101], s[38:39] op_sel_hi:[1,0]
	v_pk_mul_f32 v[14:15], v[98:99], s[38:39] op_sel_hi:[1,0]
	v_pk_mul_f32 v[6:7], v[102:103], s[38:39] op_sel_hi:[1,0]
	v_pk_mul_f32 v[8:9], v[104:105], s[38:39] op_sel_hi:[1,0]
	v_cvt_pk_bf16_f32 v6, v6, v7
	s_nop 0
	v_cvt_pk_bf16_f32 v7, v8, v9
	v_cvt_pk_bf16_f32 v8, v14, v15
	v_cvt_pk_bf16_f32 v9, v12, v13
	global_store_dwordx4 v[10:11], v[6:9], off offset:256
	v_pk_mul_f32 v[12:13], v[92:93], s[38:39] op_sel_hi:[1,0]
	v_pk_mul_f32 v[14:15], v[90:91], s[38:39] op_sel_hi:[1,0]
	v_add_u32_e32 v6, 0x80, v16
	v_mad_i64_i32 v[6:7], s[8:9], v6, s95, v[2:3]
	v_lshl_add_u64 v[10:11], v[6:7], 0, v[4:5]
	v_pk_mul_f32 v[6:7], v[94:95], s[38:39] op_sel_hi:[1,0]
	v_pk_mul_f32 v[8:9], v[96:97], s[38:39] op_sel_hi:[1,0]
	v_cvt_pk_bf16_f32 v6, v6, v7
	s_nop 0
	v_cvt_pk_bf16_f32 v7, v8, v9
	v_cvt_pk_bf16_f32 v8, v14, v15
	v_cvt_pk_bf16_f32 v9, v12, v13
	global_store_dwordx4 v[10:11], v[6:9], off nt
	v_pk_mul_f32 v[12:13], v[60:61], s[38:39] op_sel_hi:[1,0]
	v_pk_mul_f32 v[14:15], v[58:59], s[38:39] op_sel_hi:[1,0]
	v_pk_mul_f32 v[6:7], v[62:63], s[38:39] op_sel_hi:[1,0]
	v_pk_mul_f32 v[8:9], v[64:65], s[38:39] op_sel_hi:[1,0]
	v_cvt_pk_bf16_f32 v6, v6, v7
	s_nop 0
	v_cvt_pk_bf16_f32 v7, v8, v9
	v_cvt_pk_bf16_f32 v8, v14, v15
	v_cvt_pk_bf16_f32 v9, v12, v13
	global_store_dwordx4 v[10:11], v[6:9], off offset:256
	v_pk_mul_f32 v[12:13], v[84:85], s[38:39] op_sel_hi:[1,0]
	v_pk_mul_f32 v[14:15], v[82:83], s[38:39] op_sel_hi:[1,0]
	v_add_u32_e32 v6, 0x90, v16
	v_mad_i64_i32 v[6:7], s[8:9], v6, s95, v[2:3]
	v_lshl_add_u64 v[10:11], v[6:7], 0, v[4:5]
	v_pk_mul_f32 v[6:7], v[86:87], s[38:39] op_sel_hi:[1,0]
	v_pk_mul_f32 v[8:9], v[88:89], s[38:39] op_sel_hi:[1,0]
	v_cvt_pk_bf16_f32 v6, v6, v7
	s_nop 0
	v_cvt_pk_bf16_f32 v7, v8, v9
	v_cvt_pk_bf16_f32 v8, v14, v15
	v_cvt_pk_bf16_f32 v9, v12, v13
	global_store_dwordx4 v[10:11], v[6:9], off nt
	v_pk_mul_f32 v[12:13], v[52:53], s[38:39] op_sel_hi:[1,0]
	v_pk_mul_f32 v[14:15], v[50:51], s[38:39] op_sel_hi:[1,0]
	v_pk_mul_f32 v[6:7], v[54:55], s[38:39] op_sel_hi:[1,0]
	v_pk_mul_f32 v[8:9], v[56:57], s[38:39] op_sel_hi:[1,0]
	v_cvt_pk_bf16_f32 v6, v6, v7
	s_nop 0
	v_cvt_pk_bf16_f32 v7, v8, v9
	v_cvt_pk_bf16_f32 v8, v14, v15
	v_cvt_pk_bf16_f32 v9, v12, v13
	global_store_dwordx4 v[10:11], v[6:9], off offset:256
	v_pk_mul_f32 v[12:13], v[76:77], s[38:39] op_sel_hi:[1,0]
	v_pk_mul_f32 v[14:15], v[74:75], s[38:39] op_sel_hi:[1,0]
	v_add_u32_e32 v6, 0xa0, v16
	v_mad_i64_i32 v[6:7], s[8:9], v6, s95, v[2:3]
	v_lshl_add_u64 v[10:11], v[6:7], 0, v[4:5]
	v_pk_mul_f32 v[6:7], v[78:79], s[38:39] op_sel_hi:[1,0]
	v_pk_mul_f32 v[8:9], v[80:81], s[38:39] op_sel_hi:[1,0]
	v_cvt_pk_bf16_f32 v6, v6, v7
	s_nop 0
	v_cvt_pk_bf16_f32 v7, v8, v9
	v_cvt_pk_bf16_f32 v8, v14, v15
	v_cvt_pk_bf16_f32 v9, v12, v13
	global_store_dwordx4 v[10:11], v[6:9], off nt
	v_pk_mul_f32 v[12:13], v[44:45], s[38:39] op_sel_hi:[1,0]
	v_pk_mul_f32 v[14:15], v[42:43], s[38:39] op_sel_hi:[1,0]
	v_pk_mul_f32 v[6:7], v[46:47], s[38:39] op_sel_hi:[1,0]
	v_pk_mul_f32 v[8:9], v[48:49], s[38:39] op_sel_hi:[1,0]
	v_cvt_pk_bf16_f32 v6, v6, v7
	s_nop 0
	v_cvt_pk_bf16_f32 v7, v8, v9
	v_cvt_pk_bf16_f32 v8, v14, v15
	v_cvt_pk_bf16_f32 v9, v12, v13
	global_store_dwordx4 v[10:11], v[6:9], off offset:256
	v_pk_mul_f32 v[10:11], v[66:67], s[38:39] op_sel_hi:[1,0]
	s_nop 0
	v_add_u32_e32 v6, 0xb0, v16
	v_mad_i64_i32 v[2:3], s[8:9], v6, s95, v[2:3]
	v_lshl_add_u64 v[6:7], v[2:3], 0, v[4:5]
	v_pk_mul_f32 v[4:5], v[72:73], s[38:39] op_sel_hi:[1,0]
	v_pk_mul_f32 v[2:3], v[70:71], s[38:39] op_sel_hi:[1,0]
	v_pk_mul_f32 v[8:9], v[68:69], s[38:39] op_sel_hi:[1,0]
	v_cvt_pk_bf16_f32 v2, v2, v3
	v_cvt_pk_bf16_f32 v3, v4, v5
	v_cvt_pk_bf16_f32 v4, v10, v11
	v_pk_mul_f32 v[10:11], v[34:35], s[38:39] op_sel_hi:[1,0]
	v_cvt_pk_bf16_f32 v5, v8, v9
	global_store_dwordx4 v[6:7], v[2:5], off nt
	v_pk_mul_f32 v[8:9], v[36:37], s[38:39] op_sel_hi:[1,0]
	s_nop 0
	v_pk_mul_f32 v[4:5], v[40:41], s[38:39] op_sel_hi:[1,0]
	v_pk_mul_f32 v[2:3], v[38:39], s[38:39] op_sel_hi:[1,0]
	s_nop 0
	v_cvt_pk_bf16_f32 v2, v2, v3
	v_cvt_pk_bf16_f32 v3, v4, v5
	v_cvt_pk_bf16_f32 v4, v10, v11
	v_cvt_pk_bf16_f32 v5, v8, v9
	global_store_dwordx4 v[6:7], v[2:5], off offset:256
	s_cbranch_vccnz .LBB0_434
	s_andn2_b64 vcc, exec, s[0:1]
	s_cbranch_vccnz .LBB0_433
	s_barrier
	s_branch .LBB0_433

.LBB0_458:
	global_store_dwordx4 v[140:141], v[126:129], off nt
	global_store_dwordx4 v[140:141], v[122:125], off offset:64
	s_nop 1
	v_add_co_u32_e32 v122, vcc, 0xc000, v140
	s_nop 1
	v_addc_co_u32_e32 v123, vcc, 0, v141, vcc
	global_store_dwordx4 v[122:123], v[118:121], off nt
	global_store_dwordx4 v[122:123], v[114:117], off offset:64
	s_nop 1
	v_add_co_u32_e32 v114, vcc, 0x18000, v140
	s_nop 1
	v_addc_co_u32_e32 v115, vcc, 0, v141, vcc
	global_store_dwordx4 v[114:115], v[110:113], off nt
	global_store_dwordx4 v[114:115], v[106:109], off offset:64
	s_nop 1
	v_add_co_u32_e32 v106, vcc, 0x24000, v140
	s_nop 1
	v_addc_co_u32_e32 v107, vcc, 0, v141, vcc
	global_store_dwordx4 v[106:107], v[102:105], off nt
	global_store_dwordx4 v[106:107], v[98:101], off offset:64
	s_nop 1
	v_add_co_u32_e32 v98, vcc, 0x60000, v140
	s_nop 1
	v_addc_co_u32_e32 v99, vcc, 0, v141, vcc
	global_store_dwordx4 v[98:99], v[94:97], off nt
	global_store_dwordx4 v[98:99], v[86:89], off offset:64
	s_nop 1
	v_add_co_u32_e32 v86, vcc, 0x6c000, v140
	s_nop 1
	v_addc_co_u32_e32 v87, vcc, 0, v141, vcc
	global_store_dwordx4 v[86:87], v[78:81], off nt
	global_store_dwordx4 v[86:87], v[70:73], off offset:64
	s_nop 1
	v_add_co_u32_e32 v70, vcc, 0x78000, v140
	s_nop 1
	v_addc_co_u32_e32 v71, vcc, 0, v141, vcc
	global_store_dwordx4 v[70:71], v[62:65], off nt
	global_store_dwordx4 v[70:71], v[54:57], off offset:64
	s_nop 1
	v_add_co_u32_e32 v54, vcc, 0x84000, v140
	s_nop 1
	v_addc_co_u32_e32 v55, vcc, 0, v141, vcc
	global_store_dwordx4 v[54:55], v[46:49], off nt
	global_store_dwordx4 v[54:55], v[38:41], off offset:64
	s_or_b32 s8, s44, 0x80
	s_cmpk_gt_i32 s8, 0x23f
	s_cbranch_scc1 .LBB0_457

.LBB0_604:
	v_lshl_or_b32 v4, s70, 8, v198
	v_ashrrev_i32_e32 v5, 31, v4
	v_lshl_add_u32 v16, s76, 8, v197
	v_mov_b64_e32 v[2:3], s[18:19]
	v_mad_i64_i32 v[6:7], s[4:5], v16, s97, v[2:3]
	v_lshlrev_b64 v[4:5], 1, v[4:5]
	v_lshl_add_u64 v[10:11], v[6:7], 0, v[4:5]
	v_pk_mul_f32 v[6:7], v[158:159], s[50:51] op_sel_hi:[1,0]
	s_nop 7
	s_nop 7
	s_nop 7
	v_pk_mul_f32 v[8:9], v[160:161], s[50:51] op_sel_hi:[1,0]
	v_cvt_pk_bf16_f32 v6, v6, v7
	v_pk_mul_f32 v[12:13], v[156:157], s[50:51] op_sel_hi:[1,0]
	v_cvt_pk_bf16_f32 v7, v8, v9
	v_pk_mul_f32 v[14:15], v[154:155], s[50:51] op_sel_hi:[1,0]
	s_andn2_b64 vcc, exec, s[2:3]
	v_cvt_pk_bf16_f32 v8, v14, v15
	v_cvt_pk_bf16_f32 v9, v12, v13
	global_store_dwordx4 v[10:11], v[6:9], off nt
	v_pk_mul_f32 v[12:13], v[124:125], s[50:51] op_sel_hi:[1,0]
	v_pk_mul_f32 v[14:15], v[122:123], s[50:51] op_sel_hi:[1,0]
	v_pk_mul_f32 v[6:7], v[126:127], s[50:51] op_sel_hi:[1,0]
	v_pk_mul_f32 v[8:9], v[128:129], s[50:51] op_sel_hi:[1,0]
	v_cvt_pk_bf16_f32 v6, v6, v7
	s_mov_b64 s[2:3], -1
	v_cvt_pk_bf16_f32 v7, v8, v9
	v_cvt_pk_bf16_f32 v8, v14, v15
	v_cvt_pk_bf16_f32 v9, v12, v13
	global_store_dwordx4 v[10:11], v[6:9], off offset:256
	v_pk_mul_f32 v[12:13], v[148:149], s[50:51] op_sel_hi:[1,0]
	v_pk_mul_f32 v[14:15], v[146:147], s[50:51] op_sel_hi:[1,0]
	v_or_b32_e32 v6, 16, v16
	v_mad_i64_i32 v[6:7], s[4:5], v6, s97, v[2:3]
	v_lshl_add_u64 v[10:11], v[6:7], 0, v[4:5]
	v_pk_mul_f32 v[6:7], v[150:151], s[50:51] op_sel_hi:[1,0]
	v_pk_mul_f32 v[8:9], v[152:153], s[50:51] op_sel_hi:[1,0]
	v_cvt_pk_bf16_f32 v6, v6, v7
	s_nop 0
	v_cvt_pk_bf16_f32 v7, v8, v9
	v_cvt_pk_bf16_f32 v8, v14, v15
	v_cvt_pk_bf16_f32 v9, v12, v13
	global_store_dwordx4 v[10:11], v[6:9], off nt
	v_pk_mul_f32 v[12:13], v[116:117], s[50:51] op_sel_hi:[1,0]
	v_pk_mul_f32 v[14:15], v[114:115], s[50:51] op_sel_hi:[1,0]
	v_pk_mul_f32 v[6:7], v[118:119], s[50:51] op_sel_hi:[1,0]
	v_pk_mul_f32 v[8:9], v[120:121], s[50:51] op_sel_hi:[1,0]
	v_cvt_pk_bf16_f32 v6, v6, v7
	s_nop 0
	v_cvt_pk_bf16_f32 v7, v8, v9
	v_cvt_pk_bf16_f32 v8, v14, v15
	v_cvt_pk_bf16_f32 v9, v12, v13
	global_store_dwordx4 v[10:11], v[6:9], off offset:256
	v_pk_mul_f32 v[12:13], v[140:141], s[50:51] op_sel_hi:[1,0]
	v_pk_mul_f32 v[14:15], v[138:139], s[50:51] op_sel_hi:[1,0]
	v_or_b32_e32 v6, 32, v16
	v_mad_i64_i32 v[6:7], s[4:5], v6, s97, v[2:3]
	v_lshl_add_u64 v[10:11], v[6:7], 0, v[4:5]
	v_pk_mul_f32 v[6:7], v[142:143], s[50:51] op_sel_hi:[1,0]
	v_pk_mul_f32 v[8:9], v[144:145], s[50:51] op_sel_hi:[1,0]
	v_cvt_pk_bf16_f32 v6, v6, v7
	s_nop 0
	v_cvt_pk_bf16_f32 v7, v8, v9
	v_cvt_pk_bf16_f32 v8, v14, v15
	v_cvt_pk_bf16_f32 v9, v12, v13
	global_store_dwordx4 v[10:11], v[6:9], off nt
	v_pk_mul_f32 v[12:13], v[108:109], s[50:51] op_sel_hi:[1,0]
	v_pk_mul_f32 v[14:15], v[106:107], s[50:51] op_sel_hi:[1,0]
	v_pk_mul_f32 v[6:7], v[110:111], s[50:51] op_sel_hi:[1,0]
	v_pk_mul_f32 v[8:9], v[112:113], s[50:51] op_sel_hi:[1,0]
	v_cvt_pk_bf16_f32 v6, v6, v7
	s_nop 0
	v_cvt_pk_bf16_f32 v7, v8, v9
	v_cvt_pk_bf16_f32 v8, v14, v15
	v_cvt_pk_bf16_f32 v9, v12, v13
	global_store_dwordx4 v[10:11], v[6:9], off offset:256
	v_pk_mul_f32 v[12:13], v[132:133], s[50:51] op_sel_hi:[1,0]
	v_pk_mul_f32 v[14:15], v[130:131], s[50:51] op_sel_hi:[1,0]
	v_or_b32_e32 v6, 48, v16
	v_mad_i64_i32 v[6:7], s[4:5], v6, s97, v[2:3]
	v_lshl_add_u64 v[10:11], v[6:7], 0, v[4:5]
	v_pk_mul_f32 v[6:7], v[134:135], s[50:51] op_sel_hi:[1,0]
	v_pk_mul_f32 v[8:9], v[136:137], s[50:51] op_sel_hi:[1,0]
	v_cvt_pk_bf16_f32 v6, v6, v7
	s_nop 0
	v_cvt_pk_bf16_f32 v7, v8, v9
	v_cvt_pk_bf16_f32 v8, v14, v15
	v_cvt_pk_bf16_f32 v9, v12, v13
	global_store_dwordx4 v[10:11], v[6:9], off nt
	v_pk_mul_f32 v[12:13], v[100:101], s[50:51] op_sel_hi:[1,0]
	v_pk_mul_f32 v[14:15], v[98:99], s[50:51] op_sel_hi:[1,0]
	v_pk_mul_f32 v[6:7], v[102:103], s[50:51] op_sel_hi:[1,0]
	v_pk_mul_f32 v[8:9], v[104:105], s[50:51] op_sel_hi:[1,0]
	v_cvt_pk_bf16_f32 v6, v6, v7
	s_nop 0
	v_cvt_pk_bf16_f32 v7, v8, v9
	v_cvt_pk_bf16_f32 v8, v14, v15
	v_cvt_pk_bf16_f32 v9, v12, v13
	global_store_dwordx4 v[10:11], v[6:9], off offset:256
	v_pk_mul_f32 v[12:13], v[92:93], s[50:51] op_sel_hi:[1,0]
	v_pk_mul_f32 v[14:15], v[90:91], s[50:51] op_sel_hi:[1,0]
	v_add_u32_e32 v6, 0x80, v16
	v_mad_i64_i32 v[6:7], s[4:5], v6, s97, v[2:3]
	v_lshl_add_u64 v[10:11], v[6:7], 0, v[4:5]
	v_pk_mul_f32 v[6:7], v[94:95], s[50:51] op_sel_hi:[1,0]
	v_pk_mul_f32 v[8:9], v[96:97], s[50:51] op_sel_hi:[1,0]
	v_cvt_pk_bf16_f32 v6, v6, v7
	s_nop 0
	v_cvt_pk_bf16_f32 v7, v8, v9
	v_cvt_pk_bf16_f32 v8, v14, v15
	v_cvt_pk_bf16_f32 v9, v12, v13
	global_store_dwordx4 v[10:11], v[6:9], off nt
	v_pk_mul_f32 v[12:13], v[60:61], s[50:51] op_sel_hi:[1,0]
	v_pk_mul_f32 v[14:15], v[58:59], s[50:51] op_sel_hi:[1,0]
	v_pk_mul_f32 v[6:7], v[62:63], s[50:51] op_sel_hi:[1,0]
	v_pk_mul_f32 v[8:9], v[64:65], s[50:51] op_sel_hi:[1,0]
	v_cvt_pk_bf16_f32 v6, v6, v7
	s_nop 0
	v_cvt_pk_bf16_f32 v7, v8, v9
	v_cvt_pk_bf16_f32 v8, v14, v15
	v_cvt_pk_bf16_f32 v9, v12, v13
	global_store_dwordx4 v[10:11], v[6:9], off offset:256
	v_pk_mul_f32 v[12:13], v[84:85], s[50:51] op_sel_hi:[1,0]
	v_pk_mul_f32 v[14:15], v[82:83], s[50:51] op_sel_hi:[1,0]
	v_add_u32_e32 v6, 0x90, v16
	v_mad_i64_i32 v[6:7], s[4:5], v6, s97, v[2:3]
	v_lshl_add_u64 v[10:11], v[6:7], 0, v[4:5]
	v_pk_mul_f32 v[6:7], v[86:87], s[50:51] op_sel_hi:[1,0]
	v_pk_mul_f32 v[8:9], v[88:89], s[50:51] op_sel_hi:[1,0]
	v_cvt_pk_bf16_f32 v6, v6, v7
	s_nop 0
	v_cvt_pk_bf16_f32 v7, v8, v9
	v_cvt_pk_bf16_f32 v8, v14, v15
	v_cvt_pk_bf16_f32 v9, v12, v13
	global_store_dwordx4 v[10:11], v[6:9], off nt
	v_pk_mul_f32 v[12:13], v[52:53], s[50:51] op_sel_hi:[1,0]
	v_pk_mul_f32 v[14:15], v[50:51], s[50:51] op_sel_hi:[1,0]
	v_pk_mul_f32 v[6:7], v[54:55], s[50:51] op_sel_hi:[1,0]
	v_pk_mul_f32 v[8:9], v[56:57], s[50:51] op_sel_hi:[1,0]
	v_cvt_pk_bf16_f32 v6, v6, v7
	s_nop 0
	v_cvt_pk_bf16_f32 v7, v8, v9
	v_cvt_pk_bf16_f32 v8, v14, v15
	v_cvt_pk_bf16_f32 v9, v12, v13
	global_store_dwordx4 v[10:11], v[6:9], off offset:256
	v_pk_mul_f32 v[12:13], v[76:77], s[50:51] op_sel_hi:[1,0]
	v_pk_mul_f32 v[14:15], v[74:75], s[50:51] op_sel_hi:[1,0]
	v_add_u32_e32 v6, 0xa0, v16
	v_mad_i64_i32 v[6:7], s[4:5], v6, s97, v[2:3]
	v_lshl_add_u64 v[10:11], v[6:7], 0, v[4:5]
	v_pk_mul_f32 v[6:7], v[78:79], s[50:51] op_sel_hi:[1,0]
	v_pk_mul_f32 v[8:9], v[80:81], s[50:51] op_sel_hi:[1,0]
	v_cvt_pk_bf16_f32 v6, v6, v7
	s_nop 0
	v_cvt_pk_bf16_f32 v7, v8, v9
	v_cvt_pk_bf16_f32 v8, v14, v15
	v_cvt_pk_bf16_f32 v9, v12, v13
	global_store_dwordx4 v[10:11], v[6:9], off nt
	v_pk_mul_f32 v[12:13], v[44:45], s[50:51] op_sel_hi:[1,0]
	v_pk_mul_f32 v[14:15], v[42:43], s[50:51] op_sel_hi:[1,0]
	v_pk_mul_f32 v[6:7], v[46:47], s[50:51] op_sel_hi:[1,0]
	v_pk_mul_f32 v[8:9], v[48:49], s[50:51] op_sel_hi:[1,0]
	v_cvt_pk_bf16_f32 v6, v6, v7
	s_nop 0
	v_cvt_pk_bf16_f32 v7, v8, v9
	v_cvt_pk_bf16_f32 v8, v14, v15
	v_cvt_pk_bf16_f32 v9, v12, v13
	global_store_dwordx4 v[10:11], v[6:9], off offset:256
	v_pk_mul_f32 v[10:11], v[66:67], s[50:51] op_sel_hi:[1,0]
	s_nop 0
	v_add_u32_e32 v6, 0xb0, v16
	v_mad_i64_i32 v[2:3], s[4:5], v6, s97, v[2:3]
	v_lshl_add_u64 v[6:7], v[2:3], 0, v[4:5]
	v_pk_mul_f32 v[4:5], v[72:73], s[50:51] op_sel_hi:[1,0]
	v_pk_mul_f32 v[2:3], v[70:71], s[50:51] op_sel_hi:[1,0]
	v_pk_mul_f32 v[8:9], v[68:69], s[50:51] op_sel_hi:[1,0]
	v_cvt_pk_bf16_f32 v2, v2, v3
	v_cvt_pk_bf16_f32 v3, v4, v5
	v_cvt_pk_bf16_f32 v4, v10, v11
	v_pk_mul_f32 v[10:11], v[34:35], s[50:51] op_sel_hi:[1,0]
	v_cvt_pk_bf16_f32 v5, v8, v9
	global_store_dwordx4 v[6:7], v[2:5], off nt
	v_pk_mul_f32 v[8:9], v[36:37], s[50:51] op_sel_hi:[1,0]
	s_nop 0
	v_pk_mul_f32 v[4:5], v[40:41], s[50:51] op_sel_hi:[1,0]
	v_pk_mul_f32 v[2:3], v[38:39], s[50:51] op_sel_hi:[1,0]
	s_nop 0
	v_cvt_pk_bf16_f32 v2, v2, v3
	v_cvt_pk_bf16_f32 v3, v4, v5
	v_cvt_pk_bf16_f32 v4, v10, v11
	v_cvt_pk_bf16_f32 v5, v8, v9
	global_store_dwordx4 v[6:7], v[2:5], off offset:256
	s_cbranch_vccnz .LBB0_597
	s_andn2_b64 vcc, exec, s[40:41]
	s_cbranch_vccnz .LBB0_596
	s_barrier
	s_branch .LBB0_596

.LBB0_618:
	v_lshl_add_u32 v8, s76, 8, v186
	v_lshl_or_b32 v2, s4, 8, v187
	v_ashrrev_i32_e32 v9, 31, v8
	v_ashrrev_i32_e32 v3, 31, v2
	v_lshlrev_b64 v[4:5], 13, v[8:9]
	v_lshl_add_u64 v[4:5], s[0:1], 0, v[4:5]
	v_lshlrev_b64 v[10:11], 1, v[2:3]
	v_lshl_add_u64 v[2:3], v[4:5], 0, v[10:11]
	v_pk_mul_f32 v[4:5], v[158:159], s[50:51] op_sel_hi:[1,0]
	s_nop 7
	s_nop 7
	s_nop 7
	v_pk_mul_f32 v[6:7], v[160:161], s[50:51] op_sel_hi:[1,0]
	v_cvt_pk_bf16_f32 v4, v4, v5
	v_pk_mul_f32 v[12:13], v[156:157], s[50:51] op_sel_hi:[1,0]
	v_cvt_pk_bf16_f32 v5, v6, v7
	v_pk_mul_f32 v[14:15], v[154:155], s[50:51] op_sel_hi:[1,0]
	v_pk_mul_f32 v[16:17], v[146:147], s[50:51] op_sel_hi:[1,0]
	v_cvt_pk_bf16_f32 v6, v14, v15
	v_cvt_pk_bf16_f32 v7, v12, v13
	global_store_dwordx4 v[2:3], v[4:7], off nt
	v_pk_mul_f32 v[12:13], v[124:125], s[50:51] op_sel_hi:[1,0]
	v_pk_mul_f32 v[14:15], v[122:123], s[50:51] op_sel_hi:[1,0]
	v_pk_mul_f32 v[4:5], v[126:127], s[50:51] op_sel_hi:[1,0]
	v_pk_mul_f32 v[6:7], v[128:129], s[50:51] op_sel_hi:[1,0]
	v_cvt_pk_bf16_f32 v4, v4, v5
	s_mov_b64 s[4:5], 0x100000
	v_cvt_pk_bf16_f32 v5, v6, v7
	v_cvt_pk_bf16_f32 v6, v14, v15
	v_cvt_pk_bf16_f32 v7, v12, v13
	global_store_dwordx4 v[2:3], v[4:7], off offset:256
	v_pk_mul_f32 v[14:15], v[148:149], s[50:51] op_sel_hi:[1,0]
	s_nop 0
	v_or_b32_e32 v4, 16, v8
	v_ashrrev_i32_e32 v5, 31, v4
	v_lshlrev_b64 v[4:5], 13, v[4:5]
	v_lshl_add_u64 v[4:5], s[0:1], 0, v[4:5]
	v_lshl_add_u64 v[12:13], v[4:5], 0, v[10:11]
	v_pk_mul_f32 v[4:5], v[150:151], s[50:51] op_sel_hi:[1,0]
	v_pk_mul_f32 v[6:7], v[152:153], s[50:51] op_sel_hi:[1,0]
	v_cvt_pk_bf16_f32 v4, v4, v5
	s_nop 0
	v_cvt_pk_bf16_f32 v5, v6, v7
	v_cvt_pk_bf16_f32 v6, v16, v17
	v_cvt_pk_bf16_f32 v7, v14, v15
	global_store_dwordx4 v[12:13], v[4:7], off nt
	v_pk_mul_f32 v[14:15], v[116:117], s[50:51] op_sel_hi:[1,0]
	v_pk_mul_f32 v[16:17], v[114:115], s[50:51] op_sel_hi:[1,0]
	v_pk_mul_f32 v[4:5], v[118:119], s[50:51] op_sel_hi:[1,0]
	v_pk_mul_f32 v[6:7], v[120:121], s[50:51] op_sel_hi:[1,0]
	v_cvt_pk_bf16_f32 v4, v4, v5
	s_nop 0
	v_cvt_pk_bf16_f32 v5, v6, v7
	v_cvt_pk_bf16_f32 v6, v16, v17
	v_cvt_pk_bf16_f32 v7, v14, v15
	global_store_dwordx4 v[12:13], v[4:7], off offset:256
	v_pk_mul_f32 v[14:15], v[140:141], s[50:51] op_sel_hi:[1,0]
	v_pk_mul_f32 v[16:17], v[138:139], s[50:51] op_sel_hi:[1,0]
	v_or_b32_e32 v4, 32, v8
	v_ashrrev_i32_e32 v5, 31, v4
	v_lshlrev_b64 v[4:5], 13, v[4:5]
	v_lshl_add_u64 v[4:5], s[0:1], 0, v[4:5]
	v_lshl_add_u64 v[12:13], v[4:5], 0, v[10:11]
	v_pk_mul_f32 v[4:5], v[142:143], s[50:51] op_sel_hi:[1,0]
	v_pk_mul_f32 v[6:7], v[144:145], s[50:51] op_sel_hi:[1,0]
	v_cvt_pk_bf16_f32 v4, v4, v5
	s_nop 0
	v_cvt_pk_bf16_f32 v5, v6, v7
	v_cvt_pk_bf16_f32 v6, v16, v17
	v_cvt_pk_bf16_f32 v7, v14, v15
	global_store_dwordx4 v[12:13], v[4:7], off nt
	v_pk_mul_f32 v[14:15], v[108:109], s[50:51] op_sel_hi:[1,0]
	v_pk_mul_f32 v[16:17], v[106:107], s[50:51] op_sel_hi:[1,0]
	v_pk_mul_f32 v[4:5], v[110:111], s[50:51] op_sel_hi:[1,0]
	v_pk_mul_f32 v[6:7], v[112:113], s[50:51] op_sel_hi:[1,0]
	v_cvt_pk_bf16_f32 v4, v4, v5
	s_nop 0
	v_cvt_pk_bf16_f32 v5, v6, v7
	v_cvt_pk_bf16_f32 v6, v16, v17
	v_cvt_pk_bf16_f32 v7, v14, v15
	global_store_dwordx4 v[12:13], v[4:7], off offset:256
	v_pk_mul_f32 v[12:13], v[130:131], s[50:51] op_sel_hi:[1,0]
	s_nop 0
	v_or_b32_e32 v4, 48, v8
	v_ashrrev_i32_e32 v5, 31, v4
	v_lshlrev_b64 v[4:5], 13, v[4:5]
	v_lshl_add_u64 v[4:5], s[0:1], 0, v[4:5]
	v_lshl_add_u64 v[8:9], v[4:5], 0, v[10:11]
	v_pk_mul_f32 v[6:7], v[136:137], s[50:51] op_sel_hi:[1,0]
	v_pk_mul_f32 v[4:5], v[134:135], s[50:51] op_sel_hi:[1,0]
	v_pk_mul_f32 v[10:11], v[132:133], s[50:51] op_sel_hi:[1,0]
	v_cvt_pk_bf16_f32 v4, v4, v5
	v_cvt_pk_bf16_f32 v5, v6, v7
	v_cvt_pk_bf16_f32 v6, v12, v13
	v_pk_mul_f32 v[12:13], v[98:99], s[50:51] op_sel_hi:[1,0]
	v_cvt_pk_bf16_f32 v7, v10, v11
	global_store_dwordx4 v[8:9], v[4:7], off nt
	v_pk_mul_f32 v[10:11], v[100:101], s[50:51] op_sel_hi:[1,0]
	s_nop 0
	v_pk_mul_f32 v[6:7], v[104:105], s[50:51] op_sel_hi:[1,0]
	v_pk_mul_f32 v[4:5], v[102:103], s[50:51] op_sel_hi:[1,0]
	s_nop 0
	v_cvt_pk_bf16_f32 v4, v4, v5
	v_cvt_pk_bf16_f32 v5, v6, v7
	v_cvt_pk_bf16_f32 v6, v12, v13
	v_cvt_pk_bf16_f32 v7, v10, v11
	global_store_dwordx4 v[8:9], v[4:7], off offset:256
	v_lshl_add_u64 v[8:9], v[2:3], 0, s[4:5]
	v_pk_mul_f32 v[10:11], v[92:93], s[50:51] op_sel_hi:[1,0]
	v_pk_mul_f32 v[6:7], v[96:97], s[50:51] op_sel_hi:[1,0]
	v_pk_mul_f32 v[4:5], v[94:95], s[50:51] op_sel_hi:[1,0]
	s_mov_b32 s4, 0x100000
	v_pk_mul_f32 v[12:13], v[90:91], s[50:51] op_sel_hi:[1,0]
	v_cvt_pk_bf16_f32 v4, v4, v5
	v_cvt_pk_bf16_f32 v5, v6, v7
	s_nop 0
	v_cvt_pk_bf16_f32 v6, v12, v13
	v_cvt_pk_bf16_f32 v7, v10, v11
	v_add_co_u32_e32 v10, vcc, s4, v2
	v_pk_mul_f32 v[12:13], v[58:59], s[50:51] op_sel_hi:[1,0]
	s_nop 0
	v_addc_co_u32_e32 v11, vcc, 0, v3, vcc
	global_store_dwordx4 v[10:11], v[4:7], off nt
	v_pk_mul_f32 v[10:11], v[60:61], s[50:51] op_sel_hi:[1,0]
	s_mov_b64 s[4:5], 0x120000
	v_pk_mul_f32 v[6:7], v[64:65], s[50:51] op_sel_hi:[1,0]
	v_pk_mul_f32 v[4:5], v[62:63], s[50:51] op_sel_hi:[1,0]
	s_nop 0
	v_cvt_pk_bf16_f32 v4, v4, v5
	v_cvt_pk_bf16_f32 v5, v6, v7
	v_cvt_pk_bf16_f32 v6, v12, v13
	v_cvt_pk_bf16_f32 v7, v10, v11
	global_store_dwordx4 v[8:9], v[4:7], off offset:256
	v_lshl_add_u64 v[8:9], v[2:3], 0, s[4:5]
	v_pk_mul_f32 v[10:11], v[84:85], s[50:51] op_sel_hi:[1,0]
	v_pk_mul_f32 v[6:7], v[88:89], s[50:51] op_sel_hi:[1,0]
	v_pk_mul_f32 v[4:5], v[86:87], s[50:51] op_sel_hi:[1,0]
	s_mov_b32 s4, 0x120000
	v_pk_mul_f32 v[12:13], v[82:83], s[50:51] op_sel_hi:[1,0]
	v_cvt_pk_bf16_f32 v4, v4, v5
	v_cvt_pk_bf16_f32 v5, v6, v7
	s_nop 0
	v_cvt_pk_bf16_f32 v6, v12, v13
	v_cvt_pk_bf16_f32 v7, v10, v11
	v_add_co_u32_e32 v10, vcc, s4, v2
	v_pk_mul_f32 v[12:13], v[50:51], s[50:51] op_sel_hi:[1,0]
	s_nop 0
	v_addc_co_u32_e32 v11, vcc, 0, v3, vcc
	global_store_dwordx4 v[10:11], v[4:7], off nt
	v_pk_mul_f32 v[10:11], v[52:53], s[50:51] op_sel_hi:[1,0]
	s_mov_b64 s[4:5], 0x140000
	v_pk_mul_f32 v[6:7], v[56:57], s[50:51] op_sel_hi:[1,0]
	v_pk_mul_f32 v[4:5], v[54:55], s[50:51] op_sel_hi:[1,0]
	s_nop 0
	v_cvt_pk_bf16_f32 v4, v4, v5
	v_cvt_pk_bf16_f32 v5, v6, v7
	v_cvt_pk_bf16_f32 v6, v12, v13
	v_cvt_pk_bf16_f32 v7, v10, v11
	global_store_dwordx4 v[8:9], v[4:7], off offset:256
	v_lshl_add_u64 v[8:9], v[2:3], 0, s[4:5]
	v_pk_mul_f32 v[10:11], v[76:77], s[50:51] op_sel_hi:[1,0]
	v_pk_mul_f32 v[6:7], v[80:81], s[50:51] op_sel_hi:[1,0]
	v_pk_mul_f32 v[4:5], v[78:79], s[50:51] op_sel_hi:[1,0]
	s_mov_b32 s4, 0x140000
	v_pk_mul_f32 v[12:13], v[74:75], s[50:51] op_sel_hi:[1,0]
	v_cvt_pk_bf16_f32 v4, v4, v5
	v_cvt_pk_bf16_f32 v5, v6, v7
	s_nop 0
	v_cvt_pk_bf16_f32 v6, v12, v13
	v_cvt_pk_bf16_f32 v7, v10, v11
	v_add_co_u32_e32 v10, vcc, s4, v2
	s_mov_b64 s[4:5], 0x160000
	s_nop 0
	v_addc_co_u32_e32 v11, vcc, 0, v3, vcc
	global_store_dwordx4 v[10:11], v[4:7], off nt
	v_pk_mul_f32 v[10:11], v[44:45], s[50:51] op_sel_hi:[1,0]
	v_pk_mul_f32 v[12:13], v[42:43], s[50:51] op_sel_hi:[1,0]
	v_pk_mul_f32 v[6:7], v[48:49], s[50:51] op_sel_hi:[1,0]
	v_pk_mul_f32 v[4:5], v[46:47], s[50:51] op_sel_hi:[1,0]
	s_nop 0
	v_cvt_pk_bf16_f32 v4, v4, v5
	v_cvt_pk_bf16_f32 v5, v6, v7
	v_cvt_pk_bf16_f32 v6, v12, v13
	v_cvt_pk_bf16_f32 v7, v10, v11
	global_store_dwordx4 v[8:9], v[4:7], off offset:256
	v_lshl_add_u64 v[8:9], v[2:3], 0, s[4:5]
	s_mov_b32 s4, 0x160000
	v_pk_mul_f32 v[4:5], v[70:71], s[50:51] op_sel_hi:[1,0]
	v_add_co_u32_e32 v2, vcc, s4, v2
	v_pk_mul_f32 v[6:7], v[72:73], s[50:51] op_sel_hi:[1,0]
	v_cvt_pk_bf16_f32 v4, v4, v5
	s_nop 0
	v_addc_co_u32_e32 v3, vcc, 0, v3, vcc
	v_cvt_pk_bf16_f32 v5, v6, v7
	v_pk_mul_f32 v[10:11], v[68:69], s[50:51] op_sel_hi:[1,0]
	v_pk_mul_f32 v[12:13], v[66:67], s[50:51] op_sel_hi:[1,0]
	s_andn2_b64 vcc, exec, s[2:3]
	v_cvt_pk_bf16_f32 v6, v12, v13
	v_cvt_pk_bf16_f32 v7, v10, v11
	global_store_dwordx4 v[2:3], v[4:7], off nt
	v_pk_mul_f32 v[2:3], v[38:39], s[50:51] op_sel_hi:[1,0]
	s_mov_b64 s[2:3], -1
	v_pk_mul_f32 v[4:5], v[40:41], s[50:51] op_sel_hi:[1,0]
	v_pk_mul_f32 v[6:7], v[36:37], s[50:51] op_sel_hi:[1,0]
	v_pk_mul_f32 v[10:11], v[34:35], s[50:51] op_sel_hi:[1,0]
	v_cvt_pk_bf16_f32 v2, v2, v3
	v_cvt_pk_bf16_f32 v3, v4, v5
	s_nop 0
	v_cvt_pk_bf16_f32 v4, v10, v11
	v_cvt_pk_bf16_f32 v5, v6, v7
	global_store_dwordx4 v[8:9], v[2:5], off offset:256
	s_cbranch_vccnz .LBB0_613
	s_andn2_b64 vcc, exec, s[38:39]
	s_cbranch_vccnz .LBB0_612
	s_barrier
	s_branch .LBB0_612

.LBB0_798:
	v_mov_b32_e32 v2, v179
	s_cmp_eq_u32 s85, 0
	s_nop 7
	s_nop 7
	s_nop 7
	s_cselect_b64 vcc, -1, 0
	v_add_u32_e32 v3, 0xffffe000, v2
	v_cndmask_b32_e32 v2, v3, v2, vcc
	v_lshl_add_u32 v2, s42, 8, v2
	s_and_b64 s[44:45], vcc, exec
	v_ashrrev_i32_e32 v3, 31, v2
	s_cselect_b32 s45, s21, s17
	s_cselect_b32 s44, s20, s16
	v_lshlrev_b64 v[2:3], 13, v[2:3]
	s_waitcnt vmcnt(0)
	v_pk_mul_f32 v[184:185], v[142:143], s[26:27] op_sel_hi:[1,0]
	v_lshl_add_u64 v[2:3], s[44:45], 0, v[2:3]
	v_pk_mul_f32 v[176:177], v[138:139], s[26:27] op_sel_hi:[1,0]
	v_pk_mul_f32 v[182:183], v[144:145], s[26:27] op_sel_hi:[1,0]
	v_pk_mul_f32 v[192:193], v[134:135], v[184:185]
	v_lshl_add_u64 v[6:7], v[172:173], 1, v[2:3]
	v_pk_mul_f32 v[172:173], v[150:151], s[26:27] op_sel_hi:[1,0]
	v_pk_mul_f32 v[174:175], v[140:141], s[26:27] op_sel_hi:[1,0]
	v_pk_mul_f32 v[186:187], v[136:137], v[182:183]
	v_pk_mul_f32 v[194:195], v[130:131], v[176:177]
	v_cvt_pk_bf16_f32 v192, v192, v193
	v_cvt_pk_bf16_f32 v193, v186, v187
	v_pk_mul_f32 v[4:5], v[146:147], s[26:27] op_sel_hi:[1,0]
	v_pk_mul_f32 v[8:9], v[152:153], s[26:27] op_sel_hi:[1,0]
	v_pk_mul_f32 v[196:197], v[132:133], v[174:175]
	v_cvt_pk_bf16_f32 v194, v194, v195
	v_pk_mul_f32 v[2:3], v[148:149], s[26:27] op_sel_hi:[1,0]
	v_cvt_pk_bf16_f32 v195, v196, v197
	global_store_dwordx4 v[6:7], v[192:195], off nt
	v_pk_mul_f32 v[186:187], v[104:105], v[8:9]
	v_pk_mul_f32 v[196:197], v[100:101], v[2:3]
	v_pk_mul_f32 v[192:193], v[102:103], v[172:173]
	v_pk_mul_f32 v[194:195], v[98:99], v[4:5]
	v_cvt_pk_bf16_f32 v192, v192, v193
	v_cvt_pk_bf16_f32 v193, v186, v187
	v_pk_mul_f32 v[186:187], v[128:129], v[182:183]
	v_cvt_pk_bf16_f32 v194, v194, v195
	v_cvt_pk_bf16_f32 v195, v196, v197
	global_store_dwordx4 v[6:7], v[192:195], off offset:256
	v_pk_mul_f32 v[196:197], v[124:125], v[174:175]
	v_pk_mul_f32 v[198:199], v[90:91], v[4:5]
	v_pk_mul_f32 v[192:193], v[126:127], v[184:185]
	v_pk_mul_f32 v[194:195], v[122:123], v[176:177]
	v_cvt_pk_bf16_f32 v192, v192, v193
	v_cvt_pk_bf16_f32 v193, v186, v187
	v_add_co_u32_e32 v186, vcc, s76, v6
	v_cvt_pk_bf16_f32 v194, v194, v195
	v_cvt_pk_bf16_f32 v195, v196, v197
	v_pk_mul_f32 v[196:197], v[92:93], v[2:3]
	s_nop 0
	v_addc_co_u32_e32 v187, vcc, 0, v7, vcc
	global_store_dwordx4 v[186:187], v[192:195], off nt
	s_nop 1
	v_pk_mul_f32 v[192:193], v[94:95], v[172:173]
	v_pk_mul_f32 v[194:195], v[96:97], v[8:9]
	v_cvt_pk_bf16_f32 v192, v192, v193
	s_nop 0
	v_cvt_pk_bf16_f32 v193, v194, v195
	v_cvt_pk_bf16_f32 v194, v198, v199
	v_cvt_pk_bf16_f32 v195, v196, v197
	global_store_dwordx4 v[186:187], v[192:195], off offset:256
	v_pk_mul_f32 v[186:187], v[120:121], v[182:183]
	v_pk_mul_f32 v[196:197], v[116:117], v[174:175]
	v_pk_mul_f32 v[192:193], v[118:119], v[184:185]
	v_pk_mul_f32 v[194:195], v[114:115], v[176:177]
	v_cvt_pk_bf16_f32 v192, v192, v193
	v_cvt_pk_bf16_f32 v193, v186, v187
	v_add_co_u32_e32 v186, vcc, s77, v6
	v_cvt_pk_bf16_f32 v194, v194, v195
	v_cvt_pk_bf16_f32 v195, v196, v197
	v_pk_mul_f32 v[196:197], v[84:85], v[2:3]
	s_nop 0
	v_addc_co_u32_e32 v187, vcc, 0, v7, vcc
	global_store_dwordx4 v[186:187], v[192:195], off nt
	v_pk_mul_f32 v[198:199], v[82:83], v[4:5]
	s_nop 0
	v_pk_mul_f32 v[192:193], v[86:87], v[172:173]
	v_pk_mul_f32 v[194:195], v[88:89], v[8:9]
	v_cvt_pk_bf16_f32 v192, v192, v193
	s_nop 0
	v_cvt_pk_bf16_f32 v193, v194, v195
	v_cvt_pk_bf16_f32 v194, v198, v199
	v_cvt_pk_bf16_f32 v195, v196, v197
	global_store_dwordx4 v[186:187], v[192:195], off offset:256
	v_pk_mul_f32 v[186:187], v[112:113], v[182:183]
	v_pk_mul_f32 v[196:197], v[108:109], v[174:175]
	v_pk_mul_f32 v[192:193], v[110:111], v[184:185]
	v_pk_mul_f32 v[194:195], v[106:107], v[176:177]
	v_cvt_pk_bf16_f32 v192, v192, v193
	v_cvt_pk_bf16_f32 v193, v186, v187
	v_add_co_u32_e32 v186, vcc, s78, v6
	v_cvt_pk_bf16_f32 v194, v194, v195
	v_cvt_pk_bf16_f32 v195, v196, v197
	v_pk_mul_f32 v[196:197], v[76:77], v[2:3]
	s_nop 0
	v_addc_co_u32_e32 v187, vcc, 0, v7, vcc
	global_store_dwordx4 v[186:187], v[192:195], off nt
	v_pk_mul_f32 v[198:199], v[74:75], v[4:5]
	s_nop 0
	v_pk_mul_f32 v[192:193], v[78:79], v[172:173]
	v_pk_mul_f32 v[194:195], v[80:81], v[8:9]
	v_cvt_pk_bf16_f32 v192, v192, v193
	s_nop 0
	v_cvt_pk_bf16_f32 v193, v194, v195
	v_cvt_pk_bf16_f32 v194, v198, v199
	v_cvt_pk_bf16_f32 v195, v196, v197
	global_store_dwordx4 v[186:187], v[192:195], off offset:256
	v_pk_mul_f32 v[186:187], v[72:73], v[182:183]
	v_pk_mul_f32 v[196:197], v[68:69], v[174:175]
	v_pk_mul_f32 v[192:193], v[70:71], v[184:185]
	v_pk_mul_f32 v[194:195], v[66:67], v[176:177]
	v_cvt_pk_bf16_f32 v192, v192, v193
	v_cvt_pk_bf16_f32 v193, v186, v187
	v_add_co_u32_e32 v186, vcc, s79, v6
	v_cvt_pk_bf16_f32 v194, v194, v195
	v_cvt_pk_bf16_f32 v195, v196, v197
	v_pk_mul_f32 v[196:197], v[36:37], v[2:3]
	s_nop 0
	v_addc_co_u32_e32 v187, vcc, 0, v7, vcc
	global_store_dwordx4 v[186:187], v[192:195], off nt
	v_pk_mul_f32 v[198:199], v[34:35], v[4:5]
	s_nop 0
	v_pk_mul_f32 v[192:193], v[38:39], v[172:173]
	v_pk_mul_f32 v[194:195], v[40:41], v[8:9]
	v_cvt_pk_bf16_f32 v192, v192, v193
	s_nop 0
	v_cvt_pk_bf16_f32 v193, v194, v195
	v_cvt_pk_bf16_f32 v194, v198, v199
	v_cvt_pk_bf16_f32 v195, v196, v197
	global_store_dwordx4 v[186:187], v[192:195], off offset:256
	v_pk_mul_f32 v[186:187], v[64:65], v[182:183]
	v_pk_mul_f32 v[196:197], v[60:61], v[174:175]
	v_pk_mul_f32 v[192:193], v[62:63], v[184:185]
	v_pk_mul_f32 v[194:195], v[58:59], v[176:177]
	v_cvt_pk_bf16_f32 v192, v192, v193
	v_cvt_pk_bf16_f32 v193, v186, v187
	v_add_co_u32_e32 v186, vcc, s80, v6
	v_cvt_pk_bf16_f32 v194, v194, v195
	v_cvt_pk_bf16_f32 v195, v196, v197
	v_pk_mul_f32 v[196:197], v[28:29], v[2:3]
	s_nop 0
	v_addc_co_u32_e32 v187, vcc, 0, v7, vcc
	global_store_dwordx4 v[186:187], v[192:195], off nt
	v_pk_mul_f32 v[198:199], v[26:27], v[4:5]
	s_nop 0
	v_pk_mul_f32 v[192:193], v[30:31], v[172:173]
	v_pk_mul_f32 v[194:195], v[32:33], v[8:9]
	v_cvt_pk_bf16_f32 v192, v192, v193
	s_nop 0
	v_cvt_pk_bf16_f32 v193, v194, v195
	v_cvt_pk_bf16_f32 v194, v198, v199
	v_cvt_pk_bf16_f32 v195, v196, v197
	global_store_dwordx4 v[186:187], v[192:195], off offset:256
	v_pk_mul_f32 v[186:187], v[56:57], v[182:183]
	v_pk_mul_f32 v[196:197], v[52:53], v[174:175]
	v_pk_mul_f32 v[192:193], v[54:55], v[184:185]
	v_pk_mul_f32 v[194:195], v[50:51], v[176:177]
	v_cvt_pk_bf16_f32 v192, v192, v193
	v_cvt_pk_bf16_f32 v193, v186, v187
	v_add_co_u32_e32 v186, vcc, s81, v6
	v_cvt_pk_bf16_f32 v194, v194, v195
	v_cvt_pk_bf16_f32 v195, v196, v197
	v_pk_mul_f32 v[196:197], v[20:21], v[2:3]
	s_nop 0
	v_addc_co_u32_e32 v187, vcc, 0, v7, vcc
	v_add_co_u32_e32 v6, vcc, s82, v6
	global_store_dwordx4 v[186:187], v[192:195], off nt
	s_nop 0
	v_addc_co_u32_e32 v7, vcc, 0, v7, vcc
	v_pk_mul_f32 v[194:195], v[24:25], v[8:9]
	v_pk_mul_f32 v[192:193], v[22:23], v[172:173]
	v_pk_mul_f32 v[198:199], v[18:19], v[4:5]
	v_cvt_pk_bf16_f32 v192, v192, v193
	v_cvt_pk_bf16_f32 v193, v194, v195
	v_pk_mul_f32 v[182:183], v[48:49], v[182:183]
	v_cvt_pk_bf16_f32 v194, v198, v199
	v_cvt_pk_bf16_f32 v195, v196, v197
	global_store_dwordx4 v[186:187], v[192:195], off offset:256
	v_pk_mul_f32 v[184:185], v[46:47], v[184:185]
	v_pk_mul_f32 v[186:187], v[44:45], v[174:175]
	v_pk_mul_f32 v[176:177], v[42:43], v[176:177]
	v_cvt_pk_bf16_f32 v174, v184, v185
	v_cvt_pk_bf16_f32 v175, v182, v183
	v_pk_mul_f32 v[4:5], v[10:11], v[4:5]
	s_and_b64 vcc, exec, s[2:3]
	s_mov_b64 s[2:3], -1
	v_cvt_pk_bf16_f32 v176, v176, v177
	v_cvt_pk_bf16_f32 v177, v186, v187
	global_store_dwordx4 v[6:7], v[174:177], off nt
	v_pk_mul_f32 v[8:9], v[16:17], v[8:9]
	v_pk_mul_f32 v[172:173], v[14:15], v[172:173]
	v_pk_mul_f32 v[174:175], v[12:13], v[2:3]
	v_cvt_pk_bf16_f32 v2, v172, v173
	v_cvt_pk_bf16_f32 v3, v8, v9
	v_cvt_pk_bf16_f32 v4, v4, v5
	s_nop 0
	v_cvt_pk_bf16_f32 v5, v174, v175
	global_store_dwordx4 v[6:7], v[2:5], off offset:256
	s_cbranch_vccnz .LBB0_778
	s_andn2_b64 vcc, exec, s[6:7]
	s_cbranch_vccnz .LBB0_777
	s_barrier
	s_branch .LBB0_777

.LBB0_950:
	v_pk_mul_f32 v[8:9], v[160:161], s[24:25] op_sel_hi:[1,0]
	v_pk_mul_f32 v[10:11], v[158:159], s[24:25] op_sel_hi:[1,0]
	v_pk_mul_f32 v[12:13], v[156:157], s[24:25] op_sel_hi:[1,0]
	v_exp_f32_e32 v8, v8
	v_exp_f32_e32 v9, v9
	v_pk_mul_f32 v[14:15], v[154:155], s[24:25] op_sel_hi:[1,0]
	v_exp_f32_e32 v10, v10
	v_exp_f32_e32 v11, v11
	v_exp_f32_e32 v12, v12
	v_exp_f32_e32 v13, v13
	v_exp_f32_e32 v14, v14
	v_exp_f32_e32 v15, v15
	v_pk_add_f32 v[8:9], v[8:9], 1.0 op_sel_hi:[1,0]
	v_pk_add_f32 v[10:11], v[10:11], 1.0 op_sel_hi:[1,0]
	v_pk_add_f32 v[12:13], v[12:13], 1.0 op_sel_hi:[1,0]
	v_rcp_f32_e32 v8, v8
	v_rcp_f32_e32 v9, v9
	v_pk_add_f32 v[14:15], v[14:15], 1.0 op_sel_hi:[1,0]
	v_rcp_f32_e32 v10, v10
	v_rcp_f32_e32 v11, v11
	v_rcp_f32_e32 v12, v12
	v_rcp_f32_e32 v13, v13
	v_rcp_f32_e32 v14, v14
	v_rcp_f32_e32 v15, v15
	v_pk_mul_f32 v[16:17], v[128:129], v[160:161]
	v_pk_mul_f32 v[18:19], v[126:127], v[158:159]
	v_pk_mul_f32 v[8:9], v[16:17], v[8:9]
	v_pk_mul_f32 v[16:17], v[124:125], v[156:157]
	v_pk_mul_f32 v[10:11], v[18:19], v[10:11]
	v_pk_mul_f32 v[18:19], v[122:123], v[154:155]
	v_pk_mul_f32 v[12:13], v[16:17], v[12:13]
	v_mov_b32_e32 v16, 0
	v_pk_mul_f32 v[14:15], v[18:19], v[14:15]
	v_cvt_scalef32_pk_fp8_f32 v16, v10, v11, s83
	v_mov_b32_e32 v17, 0
	v_cvt_scalef32_pk_fp8_f32 v16, v8, v9, s83 op_sel:[0,0,0,1]
	v_cvt_scalef32_pk_fp8_f32 v17, v14, v15, s83
	v_pk_mul_f32 v[8:9], v[152:153], s[24:25] op_sel_hi:[1,0]
	v_cvt_scalef32_pk_fp8_f32 v17, v12, v13, s83 op_sel:[0,0,0,1]
	v_pk_mul_f32 v[10:11], v[150:151], s[24:25] op_sel_hi:[1,0]
	v_pk_mul_f32 v[12:13], v[148:149], s[24:25] op_sel_hi:[1,0]
	v_exp_f32_e32 v8, v8
	v_exp_f32_e32 v9, v9
	v_pk_mul_f32 v[14:15], v[146:147], s[24:25] op_sel_hi:[1,0]
	v_exp_f32_e32 v10, v10
	v_exp_f32_e32 v11, v11
	v_exp_f32_e32 v12, v12
	v_exp_f32_e32 v13, v13
	v_exp_f32_e32 v14, v14
	v_exp_f32_e32 v15, v15
	v_mov_b32_e32 v2, v163
	s_nop 7
	s_nop 7
	s_nop 7
	v_pk_add_f32 v[8:9], v[8:9], 1.0 op_sel_hi:[1,0]
	v_lshl_add_u32 v20, s42, 8, v2
	v_lshl_or_b32 v2, s33, 7, v179
	v_mov_b64_e32 v[4:5], s[12:13]
	v_pk_add_f32 v[10:11], v[10:11], 1.0 op_sel_hi:[1,0]
	v_pk_add_f32 v[12:13], v[12:13], 1.0 op_sel_hi:[1,0]
	v_rcp_f32_e32 v8, v8
	v_rcp_f32_e32 v9, v9
	v_ashrrev_i32_e32 v3, 31, v2
	v_mad_i64_i32 v[6:7], s[44:45], v20, s82, v[4:5]
	v_pk_add_f32 v[14:15], v[14:15], 1.0 op_sel_hi:[1,0]
	v_rcp_f32_e32 v10, v10
	v_rcp_f32_e32 v11, v11
	v_rcp_f32_e32 v12, v12
	v_rcp_f32_e32 v13, v13
	v_lshl_add_u64 v[6:7], v[6:7], 0, v[2:3]
	v_rcp_f32_e32 v14, v14
	v_rcp_f32_e32 v15, v15
	global_store_dwordx2 v[6:7], v[16:17], off nt
	v_pk_mul_f32 v[16:17], v[120:121], v[152:153]
	v_pk_mul_f32 v[18:19], v[118:119], v[150:151]
	v_pk_mul_f32 v[8:9], v[16:17], v[8:9]
	v_pk_mul_f32 v[16:17], v[116:117], v[148:149]
	v_pk_mul_f32 v[10:11], v[18:19], v[10:11]
	v_pk_mul_f32 v[18:19], v[114:115], v[146:147]
	v_pk_mul_f32 v[12:13], v[16:17], v[12:13]
	v_mov_b32_e32 v16, 0
	v_pk_mul_f32 v[14:15], v[18:19], v[14:15]
	v_cvt_scalef32_pk_fp8_f32 v16, v10, v11, s83
	v_mov_b32_e32 v17, 0
	v_cvt_scalef32_pk_fp8_f32 v16, v8, v9, s83 op_sel:[0,0,0,1]
	v_cvt_scalef32_pk_fp8_f32 v17, v14, v15, s83
	v_pk_mul_f32 v[8:9], v[144:145], s[24:25] op_sel_hi:[1,0]
	v_cvt_scalef32_pk_fp8_f32 v17, v12, v13, s83 op_sel:[0,0,0,1]
	v_pk_mul_f32 v[10:11], v[142:143], s[24:25] op_sel_hi:[1,0]
	v_pk_mul_f32 v[12:13], v[140:141], s[24:25] op_sel_hi:[1,0]
	v_exp_f32_e32 v8, v8
	v_exp_f32_e32 v9, v9
	v_pk_mul_f32 v[14:15], v[138:139], s[24:25] op_sel_hi:[1,0]
	v_exp_f32_e32 v10, v10
	v_exp_f32_e32 v11, v11
	v_exp_f32_e32 v12, v12
	v_exp_f32_e32 v13, v13
	v_exp_f32_e32 v14, v14
	v_exp_f32_e32 v15, v15
	v_pk_add_f32 v[8:9], v[8:9], 1.0 op_sel_hi:[1,0]
	v_add_u32_e32 v6, 16, v20
	v_pk_add_f32 v[10:11], v[10:11], 1.0 op_sel_hi:[1,0]
	v_pk_add_f32 v[12:13], v[12:13], 1.0 op_sel_hi:[1,0]
	v_rcp_f32_e32 v8, v8
	v_rcp_f32_e32 v9, v9
	v_mad_i64_i32 v[6:7], s[44:45], v6, s82, v[4:5]
	v_pk_add_f32 v[14:15], v[14:15], 1.0 op_sel_hi:[1,0]
	v_rcp_f32_e32 v10, v10
	v_rcp_f32_e32 v11, v11
	v_rcp_f32_e32 v12, v12
	v_rcp_f32_e32 v13, v13
	v_lshl_add_u64 v[6:7], v[6:7], 0, v[2:3]
	v_rcp_f32_e32 v14, v14
	v_rcp_f32_e32 v15, v15
	global_store_dwordx2 v[6:7], v[16:17], off nt
	v_pk_mul_f32 v[16:17], v[112:113], v[144:145]
	v_pk_mul_f32 v[18:19], v[110:111], v[142:143]
	v_pk_mul_f32 v[8:9], v[16:17], v[8:9]
	v_pk_mul_f32 v[16:17], v[108:109], v[140:141]
	v_pk_mul_f32 v[10:11], v[18:19], v[10:11]
	v_pk_mul_f32 v[18:19], v[106:107], v[138:139]
	v_pk_mul_f32 v[12:13], v[16:17], v[12:13]
	v_mov_b32_e32 v16, 0
	v_pk_mul_f32 v[14:15], v[18:19], v[14:15]
	v_cvt_scalef32_pk_fp8_f32 v16, v10, v11, s83
	v_mov_b32_e32 v17, 0
	v_cvt_scalef32_pk_fp8_f32 v16, v8, v9, s83 op_sel:[0,0,0,1]
	v_cvt_scalef32_pk_fp8_f32 v17, v14, v15, s83
	v_pk_mul_f32 v[8:9], v[136:137], s[24:25] op_sel_hi:[1,0]
	v_cvt_scalef32_pk_fp8_f32 v17, v12, v13, s83 op_sel:[0,0,0,1]
	v_pk_mul_f32 v[10:11], v[134:135], s[24:25] op_sel_hi:[1,0]
	v_pk_mul_f32 v[12:13], v[132:133], s[24:25] op_sel_hi:[1,0]
	v_exp_f32_e32 v8, v8
	v_exp_f32_e32 v9, v9
	v_pk_mul_f32 v[14:15], v[130:131], s[24:25] op_sel_hi:[1,0]
	v_exp_f32_e32 v10, v10
	v_exp_f32_e32 v11, v11
	v_exp_f32_e32 v12, v12
	v_exp_f32_e32 v13, v13
	v_exp_f32_e32 v14, v14
	v_exp_f32_e32 v15, v15
	v_pk_add_f32 v[8:9], v[8:9], 1.0 op_sel_hi:[1,0]
	v_add_u32_e32 v6, 32, v20
	v_pk_add_f32 v[10:11], v[10:11], 1.0 op_sel_hi:[1,0]
	v_pk_add_f32 v[12:13], v[12:13], 1.0 op_sel_hi:[1,0]
	v_rcp_f32_e32 v8, v8
	v_rcp_f32_e32 v9, v9
	v_mad_i64_i32 v[6:7], s[44:45], v6, s82, v[4:5]
	v_pk_add_f32 v[14:15], v[14:15], 1.0 op_sel_hi:[1,0]
	v_rcp_f32_e32 v10, v10
	v_rcp_f32_e32 v11, v11
	v_rcp_f32_e32 v12, v12
	v_rcp_f32_e32 v13, v13
	v_lshl_add_u64 v[6:7], v[6:7], 0, v[2:3]
	v_rcp_f32_e32 v14, v14
	v_rcp_f32_e32 v15, v15
	global_store_dwordx2 v[6:7], v[16:17], off nt
	v_pk_mul_f32 v[16:17], v[104:105], v[136:137]
	v_pk_mul_f32 v[18:19], v[102:103], v[134:135]
	v_pk_mul_f32 v[8:9], v[16:17], v[8:9]
	v_pk_mul_f32 v[16:17], v[100:101], v[132:133]
	v_pk_mul_f32 v[10:11], v[18:19], v[10:11]
	v_pk_mul_f32 v[18:19], v[98:99], v[130:131]
	v_pk_mul_f32 v[12:13], v[16:17], v[12:13]
	v_mov_b32_e32 v16, 0
	v_pk_mul_f32 v[14:15], v[18:19], v[14:15]
	v_cvt_scalef32_pk_fp8_f32 v16, v10, v11, s83
	v_mov_b32_e32 v17, 0
	v_cvt_scalef32_pk_fp8_f32 v16, v8, v9, s83 op_sel:[0,0,0,1]
	v_cvt_scalef32_pk_fp8_f32 v17, v14, v15, s83
	v_pk_mul_f32 v[8:9], v[96:97], s[24:25] op_sel_hi:[1,0]
	v_cvt_scalef32_pk_fp8_f32 v17, v12, v13, s83 op_sel:[0,0,0,1]
	v_pk_mul_f32 v[10:11], v[94:95], s[24:25] op_sel_hi:[1,0]
	v_pk_mul_f32 v[12:13], v[92:93], s[24:25] op_sel_hi:[1,0]
	v_exp_f32_e32 v8, v8
	v_exp_f32_e32 v9, v9
	v_pk_mul_f32 v[14:15], v[90:91], s[24:25] op_sel_hi:[1,0]
	v_exp_f32_e32 v10, v10
	v_exp_f32_e32 v11, v11
	v_exp_f32_e32 v12, v12
	v_exp_f32_e32 v13, v13
	v_exp_f32_e32 v14, v14
	v_exp_f32_e32 v15, v15
	v_pk_add_f32 v[8:9], v[8:9], 1.0 op_sel_hi:[1,0]
	v_add_u32_e32 v6, 48, v20
	v_pk_add_f32 v[10:11], v[10:11], 1.0 op_sel_hi:[1,0]
	v_pk_add_f32 v[12:13], v[12:13], 1.0 op_sel_hi:[1,0]
	v_rcp_f32_e32 v8, v8
	v_rcp_f32_e32 v9, v9
	v_mad_i64_i32 v[6:7], s[44:45], v6, s82, v[4:5]
	v_pk_add_f32 v[14:15], v[14:15], 1.0 op_sel_hi:[1,0]
	v_rcp_f32_e32 v10, v10
	v_rcp_f32_e32 v11, v11
	v_rcp_f32_e32 v12, v12
	v_rcp_f32_e32 v13, v13
	v_lshl_add_u64 v[6:7], v[6:7], 0, v[2:3]
	v_rcp_f32_e32 v14, v14
	v_rcp_f32_e32 v15, v15
	global_store_dwordx2 v[6:7], v[16:17], off nt
	v_pk_mul_f32 v[16:17], v[64:65], v[96:97]
	v_pk_mul_f32 v[18:19], v[62:63], v[94:95]
	v_pk_mul_f32 v[8:9], v[16:17], v[8:9]
	v_pk_mul_f32 v[16:17], v[60:61], v[92:93]
	v_pk_mul_f32 v[10:11], v[18:19], v[10:11]
	v_pk_mul_f32 v[18:19], v[58:59], v[90:91]
	v_pk_mul_f32 v[12:13], v[16:17], v[12:13]
	v_mov_b32_e32 v16, 0
	v_pk_mul_f32 v[14:15], v[18:19], v[14:15]
	v_cvt_scalef32_pk_fp8_f32 v16, v10, v11, s83
	v_mov_b32_e32 v17, 0
	v_cvt_scalef32_pk_fp8_f32 v16, v8, v9, s83 op_sel:[0,0,0,1]
	v_cvt_scalef32_pk_fp8_f32 v17, v14, v15, s83
	v_pk_mul_f32 v[8:9], v[88:89], s[24:25] op_sel_hi:[1,0]
	v_cvt_scalef32_pk_fp8_f32 v17, v12, v13, s83 op_sel:[0,0,0,1]
	v_pk_mul_f32 v[10:11], v[86:87], s[24:25] op_sel_hi:[1,0]
	v_pk_mul_f32 v[12:13], v[84:85], s[24:25] op_sel_hi:[1,0]
	v_exp_f32_e32 v8, v8
	v_exp_f32_e32 v9, v9
	v_pk_mul_f32 v[14:15], v[82:83], s[24:25] op_sel_hi:[1,0]
	v_exp_f32_e32 v10, v10
	v_exp_f32_e32 v11, v11
	v_exp_f32_e32 v12, v12
	v_exp_f32_e32 v13, v13
	v_exp_f32_e32 v14, v14
	v_exp_f32_e32 v15, v15
	v_pk_add_f32 v[8:9], v[8:9], 1.0 op_sel_hi:[1,0]
	v_add_u32_e32 v6, 0x80, v20
	v_pk_add_f32 v[10:11], v[10:11], 1.0 op_sel_hi:[1,0]
	v_pk_add_f32 v[12:13], v[12:13], 1.0 op_sel_hi:[1,0]
	v_rcp_f32_e32 v8, v8
	v_rcp_f32_e32 v9, v9
	v_mad_i64_i32 v[6:7], s[44:45], v6, s82, v[4:5]
	v_pk_add_f32 v[14:15], v[14:15], 1.0 op_sel_hi:[1,0]
	v_rcp_f32_e32 v10, v10
	v_rcp_f32_e32 v11, v11
	v_rcp_f32_e32 v12, v12
	v_rcp_f32_e32 v13, v13
	v_lshl_add_u64 v[6:7], v[6:7], 0, v[2:3]
	v_rcp_f32_e32 v14, v14
	v_rcp_f32_e32 v15, v15
	global_store_dwordx2 v[6:7], v[16:17], off nt
	v_pk_mul_f32 v[16:17], v[56:57], v[88:89]
	v_pk_mul_f32 v[18:19], v[54:55], v[86:87]
	v_pk_mul_f32 v[8:9], v[16:17], v[8:9]
	v_pk_mul_f32 v[16:17], v[52:53], v[84:85]
	v_pk_mul_f32 v[10:11], v[18:19], v[10:11]
	v_pk_mul_f32 v[18:19], v[50:51], v[82:83]
	v_pk_mul_f32 v[12:13], v[16:17], v[12:13]
	v_mov_b32_e32 v16, 0
	v_pk_mul_f32 v[14:15], v[18:19], v[14:15]
	v_cvt_scalef32_pk_fp8_f32 v16, v10, v11, s83
	v_mov_b32_e32 v17, 0
	v_cvt_scalef32_pk_fp8_f32 v16, v8, v9, s83 op_sel:[0,0,0,1]
	v_cvt_scalef32_pk_fp8_f32 v17, v14, v15, s83
	v_pk_mul_f32 v[8:9], v[80:81], s[24:25] op_sel_hi:[1,0]
	v_pk_mul_f32 v[10:11], v[78:79], s[24:25] op_sel_hi:[1,0]
	v_cvt_scalef32_pk_fp8_f32 v17, v12, v13, s83 op_sel:[0,0,0,1]
	v_pk_mul_f32 v[12:13], v[76:77], s[24:25] op_sel_hi:[1,0]
	v_pk_mul_f32 v[14:15], v[74:75], s[24:25] op_sel_hi:[1,0]
	v_exp_f32_e32 v10, v10
	v_exp_f32_e32 v11, v11
	v_exp_f32_e32 v8, v8
	v_exp_f32_e32 v9, v9
	v_exp_f32_e32 v14, v14
	v_exp_f32_e32 v12, v12
	v_exp_f32_e32 v13, v13
	v_exp_f32_e32 v15, v15
	v_pk_add_f32 v[8:9], v[8:9], 1.0 op_sel_hi:[1,0]
	v_pk_add_f32 v[10:11], v[10:11], 1.0 op_sel_hi:[1,0]
	v_add_u32_e32 v6, 0x90, v20
	v_pk_add_f32 v[12:13], v[12:13], 1.0 op_sel_hi:[1,0]
	v_pk_add_f32 v[14:15], v[14:15], 1.0 op_sel_hi:[1,0]
	v_rcp_f32_e32 v10, v10
	v_rcp_f32_e32 v11, v11
	v_rcp_f32_e32 v8, v8
	v_rcp_f32_e32 v9, v9
	v_mad_i64_i32 v[6:7], s[44:45], v6, s82, v[4:5]
	v_rcp_f32_e32 v14, v14
	v_rcp_f32_e32 v15, v15
	v_rcp_f32_e32 v12, v12
	v_rcp_f32_e32 v13, v13
	v_lshl_add_u64 v[6:7], v[6:7], 0, v[2:3]
	global_store_dwordx2 v[6:7], v[16:17], off nt
	v_pk_mul_f32 v[16:17], v[48:49], v[80:81]
	v_pk_mul_f32 v[18:19], v[46:47], v[78:79]
	v_pk_mul_f32 v[8:9], v[16:17], v[8:9]
	v_pk_mul_f32 v[10:11], v[18:19], v[10:11]
	v_pk_mul_f32 v[16:17], v[44:45], v[76:77]
	v_pk_mul_f32 v[18:19], v[42:43], v[74:75]
	v_add_u32_e32 v6, 0xa0, v20
	v_pk_mul_f32 v[12:13], v[16:17], v[12:13]
	v_pk_mul_f32 v[14:15], v[18:19], v[14:15]
	v_mov_b32_e32 v16, 0
	v_mov_b32_e32 v17, 0
	v_mad_i64_i32 v[6:7], s[44:45], v6, s82, v[4:5]
	v_cvt_scalef32_pk_fp8_f32 v16, v10, v11, s83
	v_cvt_scalef32_pk_fp8_f32 v17, v14, v15, s83
	v_lshl_add_u64 v[6:7], v[6:7], 0, v[2:3]
	v_cvt_scalef32_pk_fp8_f32 v16, v8, v9, s83 op_sel:[0,0,0,1]
	v_cvt_scalef32_pk_fp8_f32 v17, v12, v13, s83 op_sel:[0,0,0,1]
	global_store_dwordx2 v[6:7], v[16:17], off nt
	v_add_u32_e32 v6, 0xb0, v20
	v_mad_i64_i32 v[4:5], s[44:45], v6, s82, v[4:5]
	v_pk_mul_f32 v[6:7], v[72:73], s[24:25] op_sel_hi:[1,0]
	v_pk_mul_f32 v[8:9], v[70:71], s[24:25] op_sel_hi:[1,0]
	v_pk_mul_f32 v[10:11], v[68:69], s[24:25] op_sel_hi:[1,0]
	v_pk_mul_f32 v[12:13], v[66:67], s[24:25] op_sel_hi:[1,0]
	v_exp_f32_e32 v8, v8
	v_exp_f32_e32 v9, v9
	v_exp_f32_e32 v6, v6
	v_exp_f32_e32 v7, v7
	v_exp_f32_e32 v12, v12
	v_exp_f32_e32 v10, v10
	v_exp_f32_e32 v11, v11
	v_exp_f32_e32 v13, v13
	v_pk_add_f32 v[6:7], v[6:7], 1.0 op_sel_hi:[1,0]
	v_pk_add_f32 v[8:9], v[8:9], 1.0 op_sel_hi:[1,0]
	v_pk_add_f32 v[10:11], v[10:11], 1.0 op_sel_hi:[1,0]
	v_pk_add_f32 v[12:13], v[12:13], 1.0 op_sel_hi:[1,0]
	v_rcp_f32_e32 v8, v8
	v_rcp_f32_e32 v9, v9
	v_rcp_f32_e32 v6, v6
	v_rcp_f32_e32 v7, v7
	v_rcp_f32_e32 v12, v12
	v_rcp_f32_e32 v13, v13
	v_rcp_f32_e32 v10, v10
	v_rcp_f32_e32 v11, v11
	v_lshl_add_u64 v[2:3], v[4:5], 0, v[2:3]
	v_pk_mul_f32 v[4:5], v[40:41], v[72:73]
	v_pk_mul_f32 v[14:15], v[38:39], v[70:71]
	v_pk_mul_f32 v[4:5], v[4:5], v[6:7]
	v_pk_mul_f32 v[6:7], v[14:15], v[8:9]
	v_pk_mul_f32 v[8:9], v[36:37], v[68:69]
	v_pk_mul_f32 v[14:15], v[34:35], v[66:67]
	v_pk_mul_f32 v[8:9], v[8:9], v[10:11]
	v_pk_mul_f32 v[10:11], v[14:15], v[12:13]
	v_mov_b32_e32 v12, 0
	v_mov_b32_e32 v13, 0
	v_cvt_scalef32_pk_fp8_f32 v12, v6, v7, s83
	v_cvt_scalef32_pk_fp8_f32 v13, v10, v11, s83
	v_cvt_scalef32_pk_fp8_f32 v12, v4, v5, s83 op_sel:[0,0,0,1]
	v_cvt_scalef32_pk_fp8_f32 v13, v8, v9, s83 op_sel:[0,0,0,1]
	s_andn2_b64 vcc, exec, s[2:3]
	s_mov_b64 s[2:3], -1
	global_store_dwordx2 v[2:3], v[12:13], off nt
	s_cbranch_vccnz .LBB0_943
	s_andn2_b64 vcc, exec, s[0:1]
	s_cbranch_vccnz .LBB0_942
	s_barrier
	s_branch .LBB0_942

.LBB0_1038:
	v_mov_b32_e32 v2, v179
	s_cmp_eq_u32 s81, 0
	s_nop 7
	s_nop 7
	s_nop 7
	s_cselect_b64 vcc, -1, 0
	v_add_u32_e32 v3, 0xffffe000, v2
	v_cndmask_b32_e32 v2, v3, v2, vcc
	v_lshl_add_u32 v2, s80, 8, v2
	s_and_b64 s[26:27], vcc, exec
	v_ashrrev_i32_e32 v3, 31, v2
	s_cselect_b32 s27, s21, s17
	s_cselect_b32 s26, s20, s16
	v_lshlrev_b64 v[2:3], 13, v[2:3]
	s_waitcnt vmcnt(0)
	v_pk_mul_f32 v[184:185], v[142:143], s[22:23] op_sel_hi:[1,0]
	v_lshl_add_u64 v[2:3], s[26:27], 0, v[2:3]
	v_pk_mul_f32 v[176:177], v[138:139], s[22:23] op_sel_hi:[1,0]
	v_pk_mul_f32 v[182:183], v[144:145], s[22:23] op_sel_hi:[1,0]
	v_pk_mul_f32 v[192:193], v[134:135], v[184:185]
	v_lshl_add_u64 v[6:7], v[172:173], 1, v[2:3]
	v_pk_mul_f32 v[172:173], v[150:151], s[22:23] op_sel_hi:[1,0]
	v_pk_mul_f32 v[174:175], v[140:141], s[22:23] op_sel_hi:[1,0]
	v_pk_mul_f32 v[186:187], v[136:137], v[182:183]
	v_pk_mul_f32 v[194:195], v[130:131], v[176:177]
	v_cvt_pk_bf16_f32 v192, v192, v193
	v_cvt_pk_bf16_f32 v193, v186, v187
	v_pk_mul_f32 v[4:5], v[146:147], s[22:23] op_sel_hi:[1,0]
	v_pk_mul_f32 v[8:9], v[152:153], s[22:23] op_sel_hi:[1,0]
	v_pk_mul_f32 v[196:197], v[132:133], v[174:175]
	v_cvt_pk_bf16_f32 v194, v194, v195
	v_pk_mul_f32 v[2:3], v[148:149], s[22:23] op_sel_hi:[1,0]
	v_cvt_pk_bf16_f32 v195, v196, v197
	global_store_dwordx4 v[6:7], v[192:195], off nt
	v_pk_mul_f32 v[186:187], v[104:105], v[8:9]
	v_pk_mul_f32 v[196:197], v[100:101], v[2:3]
	v_pk_mul_f32 v[192:193], v[102:103], v[172:173]
	v_pk_mul_f32 v[194:195], v[98:99], v[4:5]
	v_cvt_pk_bf16_f32 v192, v192, v193
	v_cvt_pk_bf16_f32 v193, v186, v187
	v_pk_mul_f32 v[186:187], v[128:129], v[182:183]
	v_cvt_pk_bf16_f32 v194, v194, v195
	v_cvt_pk_bf16_f32 v195, v196, v197
	global_store_dwordx4 v[6:7], v[192:195], off offset:256
	v_pk_mul_f32 v[196:197], v[124:125], v[174:175]
	v_pk_mul_f32 v[198:199], v[90:91], v[4:5]
	v_pk_mul_f32 v[192:193], v[126:127], v[184:185]
	v_pk_mul_f32 v[194:195], v[122:123], v[176:177]
	v_cvt_pk_bf16_f32 v192, v192, v193
	v_cvt_pk_bf16_f32 v193, v186, v187
	v_add_co_u32_e32 v186, vcc, s61, v6
	v_cvt_pk_bf16_f32 v194, v194, v195
	v_cvt_pk_bf16_f32 v195, v196, v197
	v_pk_mul_f32 v[196:197], v[92:93], v[2:3]
	s_nop 0
	v_addc_co_u32_e32 v187, vcc, 0, v7, vcc
	global_store_dwordx4 v[186:187], v[192:195], off nt
	s_nop 1
	v_pk_mul_f32 v[192:193], v[94:95], v[172:173]
	v_pk_mul_f32 v[194:195], v[96:97], v[8:9]
	v_cvt_pk_bf16_f32 v192, v192, v193
	s_nop 0
	v_cvt_pk_bf16_f32 v193, v194, v195
	v_cvt_pk_bf16_f32 v194, v198, v199
	v_cvt_pk_bf16_f32 v195, v196, v197
	global_store_dwordx4 v[186:187], v[192:195], off offset:256
	v_pk_mul_f32 v[186:187], v[120:121], v[182:183]
	v_pk_mul_f32 v[196:197], v[116:117], v[174:175]
	v_pk_mul_f32 v[192:193], v[118:119], v[184:185]
	v_pk_mul_f32 v[194:195], v[114:115], v[176:177]
	v_cvt_pk_bf16_f32 v192, v192, v193
	v_cvt_pk_bf16_f32 v193, v186, v187
	v_add_co_u32_e32 v186, vcc, s68, v6
	v_cvt_pk_bf16_f32 v194, v194, v195
	v_cvt_pk_bf16_f32 v195, v196, v197
	v_pk_mul_f32 v[196:197], v[84:85], v[2:3]
	s_nop 0
	v_addc_co_u32_e32 v187, vcc, 0, v7, vcc
	global_store_dwordx4 v[186:187], v[192:195], off nt
	v_pk_mul_f32 v[198:199], v[82:83], v[4:5]
	s_nop 0
	v_pk_mul_f32 v[192:193], v[86:87], v[172:173]
	v_pk_mul_f32 v[194:195], v[88:89], v[8:9]
	v_cvt_pk_bf16_f32 v192, v192, v193
	s_nop 0
	v_cvt_pk_bf16_f32 v193, v194, v195
	v_cvt_pk_bf16_f32 v194, v198, v199
	v_cvt_pk_bf16_f32 v195, v196, v197
	global_store_dwordx4 v[186:187], v[192:195], off offset:256
	v_pk_mul_f32 v[186:187], v[112:113], v[182:183]
	v_pk_mul_f32 v[196:197], v[108:109], v[174:175]
	v_pk_mul_f32 v[192:193], v[110:111], v[184:185]
	v_pk_mul_f32 v[194:195], v[106:107], v[176:177]
	v_cvt_pk_bf16_f32 v192, v192, v193
	v_cvt_pk_bf16_f32 v193, v186, v187
	v_add_co_u32_e32 v186, vcc, s69, v6
	v_cvt_pk_bf16_f32 v194, v194, v195
	v_cvt_pk_bf16_f32 v195, v196, v197
	v_pk_mul_f32 v[196:197], v[76:77], v[2:3]
	s_nop 0
	v_addc_co_u32_e32 v187, vcc, 0, v7, vcc
	global_store_dwordx4 v[186:187], v[192:195], off nt
	v_pk_mul_f32 v[198:199], v[74:75], v[4:5]
	s_nop 0
	v_pk_mul_f32 v[192:193], v[78:79], v[172:173]
	v_pk_mul_f32 v[194:195], v[80:81], v[8:9]
	v_cvt_pk_bf16_f32 v192, v192, v193
	s_nop 0
	v_cvt_pk_bf16_f32 v193, v194, v195
	v_cvt_pk_bf16_f32 v194, v198, v199
	v_cvt_pk_bf16_f32 v195, v196, v197
	global_store_dwordx4 v[186:187], v[192:195], off offset:256
	v_pk_mul_f32 v[186:187], v[72:73], v[182:183]
	v_pk_mul_f32 v[196:197], v[68:69], v[174:175]
	v_pk_mul_f32 v[192:193], v[70:71], v[184:185]
	v_pk_mul_f32 v[194:195], v[66:67], v[176:177]
	v_cvt_pk_bf16_f32 v192, v192, v193
	v_cvt_pk_bf16_f32 v193, v186, v187
	v_add_co_u32_e32 v186, vcc, s72, v6
	v_cvt_pk_bf16_f32 v194, v194, v195
	v_cvt_pk_bf16_f32 v195, v196, v197
	v_pk_mul_f32 v[196:197], v[36:37], v[2:3]
	s_nop 0
	v_addc_co_u32_e32 v187, vcc, 0, v7, vcc
	global_store_dwordx4 v[186:187], v[192:195], off nt
	v_pk_mul_f32 v[198:199], v[34:35], v[4:5]
	s_nop 0
	v_pk_mul_f32 v[192:193], v[38:39], v[172:173]
	v_pk_mul_f32 v[194:195], v[40:41], v[8:9]
	v_cvt_pk_bf16_f32 v192, v192, v193
	s_nop 0
	v_cvt_pk_bf16_f32 v193, v194, v195
	v_cvt_pk_bf16_f32 v194, v198, v199
	v_cvt_pk_bf16_f32 v195, v196, v197
	global_store_dwordx4 v[186:187], v[192:195], off offset:256
	v_pk_mul_f32 v[186:187], v[64:65], v[182:183]
	v_pk_mul_f32 v[196:197], v[60:61], v[174:175]
	v_pk_mul_f32 v[192:193], v[62:63], v[184:185]
	v_pk_mul_f32 v[194:195], v[58:59], v[176:177]
	v_cvt_pk_bf16_f32 v192, v192, v193
	v_cvt_pk_bf16_f32 v193, v186, v187
	v_add_co_u32_e32 v186, vcc, s73, v6
	v_cvt_pk_bf16_f32 v194, v194, v195
	v_cvt_pk_bf16_f32 v195, v196, v197
	v_pk_mul_f32 v[196:197], v[28:29], v[2:3]
	s_nop 0
	v_addc_co_u32_e32 v187, vcc, 0, v7, vcc
	global_store_dwordx4 v[186:187], v[192:195], off nt
	v_pk_mul_f32 v[198:199], v[26:27], v[4:5]
	s_nop 0
	v_pk_mul_f32 v[192:193], v[30:31], v[172:173]
	v_pk_mul_f32 v[194:195], v[32:33], v[8:9]
	v_cvt_pk_bf16_f32 v192, v192, v193
	s_nop 0
	v_cvt_pk_bf16_f32 v193, v194, v195
	v_cvt_pk_bf16_f32 v194, v198, v199
	v_cvt_pk_bf16_f32 v195, v196, v197
	global_store_dwordx4 v[186:187], v[192:195], off offset:256
	v_pk_mul_f32 v[186:187], v[56:57], v[182:183]
	v_pk_mul_f32 v[196:197], v[52:53], v[174:175]
	v_pk_mul_f32 v[192:193], v[54:55], v[184:185]
	v_pk_mul_f32 v[194:195], v[50:51], v[176:177]
	v_cvt_pk_bf16_f32 v192, v192, v193
	v_cvt_pk_bf16_f32 v193, v186, v187
	v_add_co_u32_e32 v186, vcc, s74, v6
	v_cvt_pk_bf16_f32 v194, v194, v195
	v_cvt_pk_bf16_f32 v195, v196, v197
	v_pk_mul_f32 v[196:197], v[20:21], v[2:3]
	s_nop 0
	v_addc_co_u32_e32 v187, vcc, 0, v7, vcc
	v_add_co_u32_e32 v6, vcc, s75, v6
	global_store_dwordx4 v[186:187], v[192:195], off nt
	s_nop 0
	v_addc_co_u32_e32 v7, vcc, 0, v7, vcc
	v_pk_mul_f32 v[194:195], v[24:25], v[8:9]
	v_pk_mul_f32 v[192:193], v[22:23], v[172:173]
	v_pk_mul_f32 v[198:199], v[18:19], v[4:5]
	v_cvt_pk_bf16_f32 v192, v192, v193
	v_cvt_pk_bf16_f32 v193, v194, v195
	v_pk_mul_f32 v[182:183], v[48:49], v[182:183]
	v_cvt_pk_bf16_f32 v194, v198, v199
	v_cvt_pk_bf16_f32 v195, v196, v197
	global_store_dwordx4 v[186:187], v[192:195], off offset:256
	v_pk_mul_f32 v[184:185], v[46:47], v[184:185]
	v_pk_mul_f32 v[186:187], v[44:45], v[174:175]
	v_pk_mul_f32 v[176:177], v[42:43], v[176:177]
	v_cvt_pk_bf16_f32 v174, v184, v185
	v_cvt_pk_bf16_f32 v175, v182, v183
	v_pk_mul_f32 v[4:5], v[10:11], v[4:5]
	s_and_b64 vcc, exec, s[2:3]
	s_mov_b64 s[2:3], -1
	v_cvt_pk_bf16_f32 v176, v176, v177
	v_cvt_pk_bf16_f32 v177, v186, v187
	global_store_dwordx4 v[6:7], v[174:177], off nt
	v_pk_mul_f32 v[8:9], v[16:17], v[8:9]
	v_pk_mul_f32 v[172:173], v[14:15], v[172:173]
	v_pk_mul_f32 v[174:175], v[12:13], v[2:3]
	v_cvt_pk_bf16_f32 v2, v172, v173
	v_cvt_pk_bf16_f32 v3, v8, v9
	v_cvt_pk_bf16_f32 v4, v4, v5
	s_nop 0
	v_cvt_pk_bf16_f32 v5, v174, v175
	global_store_dwordx4 v[6:7], v[2:5], off offset:256
	s_cbranch_vccnz .LBB0_1018
	s_andn2_b64 vcc, exec, s[6:7]
	s_cbranch_vccnz .LBB0_1017
	s_barrier
	s_branch .LBB0_1017
